# out-proj residual folded into the accumulators during the K-loop (1/16 slice per iteration, acc += x/ra with plain f32 fmac), load-free epilogue; plus tile order, sink s_load, transpose load loops unr
# speedup vs baseline: 1.0064x; 1.0064x over previous
; template <bool MAPIN>
; __device__ __forceinline__ void transpose_item(const float* W, int K, int N, bf16_t* WT, LAS float* scr, int item, int lane, const float* gk = nullptr) {
;     const int nblk = N / 32, kb = item / nblk, nb = item % nblk, k0 = 64 * kb, n0 = 32 * nb;
; #pragma unroll 8
;     for (int i = 0; i < 32; ++i) { const int kk = 2 * i + (lane >> 5); scr[kk * 33 + (lane & 31)] = W[(size_t)(k0 + kk) * N + n0 + (lane & 31)]; }
.LBB0_108:
	s_lshl_b32 s19, s16, 1
	s_lshl_b32 s20, s17, 1
	v_or_b32_e32 v14, s20, v4
	s_add_i32 s22, s19, 4
	s_add_i32 s23, s20, 4
	v_mov_b32_e32 v9, v15
	s_add_i32 s25, s20, 8
	v_lshlrev_b64 v[48:49], 13, v[14:15]
	v_or_b32_e32 v8, s22, v5
	v_or_b32_e32 v14, s23, v4
	v_mov_b32_e32 v7, v15
	v_or_b32_e32 v6, s19, v5
	s_add_i32 s27, s20, 12
	v_lshlrev_b64 v[8:9], 13, v[8:9]
	v_lshlrev_b64 v[50:51], 13, v[14:15]
	v_or_b32_e32 v14, s25, v4
	s_add_i32 s24, s19, 8
	s_add_i32 s26, s19, 12
	s_add_i32 s29, s20, 16
	v_lshlrev_b64 v[6:7], 13, v[6:7]
	v_lshl_add_u64 v[48:49], v[2:3], 0, v[48:49]
	v_lshl_add_u64 v[8:9], v[2:3], 0, v[8:9]
	v_lshlrev_b64 v[52:53], 13, v[14:15]
	v_or_b32_e32 v14, s27, v4
	v_mov_b32_e32 v23, v15
	v_mov_b32_e32 v39, v15
	s_add_i32 s31, s20, 20
	v_or_b32_e32 v22, s24, v5
	v_or_b32_e32 v38, s26, v5
	v_lshl_add_u64 v[6:7], v[2:3], 0, v[6:7]
	v_lshl_add_u64 v[50:51], v[2:3], 0, v[50:51]
	global_load_dword v21, v[48:49], off
	global_load_dword v25, v[6:7], off
	global_load_dword v65, v[50:51], off
	global_load_dword v67, v[8:9], off
	v_lshlrev_b64 v[8:9], 13, v[14:15]
	v_or_b32_e32 v14, s29, v4
	s_add_i32 s28, s19, 16
	s_add_i32 s30, s19, 20
	s_add_i32 s35, s20, 24
	v_lshlrev_b64 v[22:23], 13, v[22:23]
	v_lshlrev_b64 v[38:39], 13, v[38:39]
	v_lshl_add_u64 v[6:7], v[2:3], 0, v[52:53]
	v_lshl_add_u64 v[8:9], v[2:3], 0, v[8:9]
	v_lshlrev_b64 v[48:49], 13, v[14:15]
	v_or_b32_e32 v14, s31, v4
	v_mov_b32_e32 v41, v15
	v_mov_b32_e32 v43, v15
	s_add_i32 s34, s19, 24
	s_add_i32 s76, s19, 28
	s_add_i32 s77, s20, 28
	v_or_b32_e32 v40, s28, v5
	v_or_b32_e32 v42, s30, v5
	v_lshl_add_u64 v[22:23], v[2:3], 0, v[22:23]
	v_lshl_add_u64 v[38:39], v[2:3], 0, v[38:39]
	global_load_dword v68, v[6:7], off
	global_load_dword v69, v[22:23], off
	global_load_dword v70, v[8:9], off
	global_load_dword v71, v[38:39], off
	v_lshlrev_b64 v[8:9], 13, v[14:15]
	v_or_b32_e32 v14, s35, v4
	v_mov_b32_e32 v45, v15
	v_mov_b32_e32 v47, v15
	v_or_b32_e32 v44, s34, v5
	v_or_b32_e32 v46, s76, v5
	v_lshlrev_b64 v[40:41], 13, v[40:41]
	v_lshlrev_b64 v[42:43], 13, v[42:43]
	v_lshl_add_u64 v[6:7], v[2:3], 0, v[48:49]
	v_lshl_add_u64 v[8:9], v[2:3], 0, v[8:9]
	v_lshlrev_b64 v[22:23], 13, v[14:15]
	v_or_b32_e32 v14, s77, v4
	v_lshlrev_b64 v[44:45], 13, v[44:45]
	v_lshlrev_b64 v[46:47], 13, v[46:47]
	v_lshl_add_u64 v[40:41], v[2:3], 0, v[40:41]
	v_lshl_add_u64 v[42:43], v[2:3], 0, v[42:43]
	global_load_dword v72, v[6:7], off
	global_load_dword v73, v[40:41], off
	global_load_dword v74, v[8:9], off
	global_load_dword v75, v[42:43], off
	v_lshl_add_u64 v[6:7], v[2:3], 0, v[22:23]
	v_lshlrev_b64 v[8:9], 13, v[14:15]
	v_lshl_add_u64 v[44:45], v[2:3], 0, v[44:45]
	v_lshl_add_u64 v[46:47], v[2:3], 0, v[46:47]
	v_lshl_add_u64 v[8:9], v[2:3], 0, v[8:9]
	global_load_dword v14, v[6:7], off
	global_load_dword v76, v[44:45], off
	global_load_dword v77, v[8:9], off
	global_load_dword v78, v[46:47], off
	v_or_b32_e32 v8, s19, v13
	v_or_b32_e32 v6, s20, v12
	s_add_i32 s17, s17, 16
	s_add_i32 s16, s16, 16
	s_add_i32 s18, s18, -16
	v_mad_u64_u32 v[6:7], s[20:21], v6, s36, v[16:17]
	v_mad_u64_u32 v[8:9], s[20:21], v8, s36, v[16:17]
	v_or_b32_e32 v7, s22, v13
	v_or_b32_e32 v9, s23, v12
	v_or_b32_e32 v42, s24, v13
	v_or_b32_e32 v40, s25, v12
	v_or_b32_e32 v46, s26, v13
	v_or_b32_e32 v44, s27, v12
	v_or_b32_e32 v50, s28, v13
	v_or_b32_e32 v48, s29, v12
	v_or_b32_e32 v54, s30, v13
	v_or_b32_e32 v52, s31, v12
	v_or_b32_e32 v58, s34, v13
	v_or_b32_e32 v56, s35, v12
	v_or_b32_e32 v62, s76, v13
	v_or_b32_e32 v60, s77, v12
	s_cmp_lg_u32 s18, 0
	v_mad_u64_u32 v[22:23], s[20:21], v9, s36, v[16:17]
	v_mad_u64_u32 v[38:39], s[20:21], v7, s36, v[16:17]
	v_mad_u64_u32 v[40:41], s[20:21], v40, s36, v[16:17]
	v_mad_u64_u32 v[42:43], s[20:21], v42, s36, v[16:17]
	v_mad_u64_u32 v[44:45], s[20:21], v44, s36, v[16:17]
	v_mad_u64_u32 v[46:47], s[20:21], v46, s36, v[16:17]
	v_mad_u64_u32 v[48:49], s[20:21], v48, s36, v[16:17]
	v_mad_u64_u32 v[50:51], s[20:21], v50, s36, v[16:17]
	v_mad_u64_u32 v[52:53], s[20:21], v52, s36, v[16:17]
	v_mad_u64_u32 v[54:55], s[20:21], v54, s36, v[16:17]
	v_mad_u64_u32 v[56:57], s[20:21], v56, s36, v[16:17]
	v_mad_u64_u32 v[58:59], s[20:21], v58, s36, v[16:17]
	v_mad_u64_u32 v[60:61], s[20:21], v60, s36, v[16:17]
	v_mad_u64_u32 v[62:63], s[20:21], v62, s36, v[16:17]
	v_mov_b32_e32 v145, v15
	s_lshl_b32 s19, s16, 1
	s_lshl_b32 s20, s17, 1
	v_or_b32_e32 v144, s20, v4
	s_add_i32 s22, s19, 4
	s_add_i32 s23, s20, 4
	v_mov_b32_e32 v139, v145
	s_add_i32 s25, s20, 8
	v_lshlrev_b64 v[178:179], 13, v[144:145]
	v_or_b32_e32 v138, s22, v5
	v_or_b32_e32 v144, s23, v4
	v_mov_b32_e32 v137, v145
	v_or_b32_e32 v136, s19, v5
	s_add_i32 s27, s20, 12
	v_lshlrev_b64 v[138:139], 13, v[138:139]
	v_lshlrev_b64 v[180:181], 13, v[144:145]
	v_or_b32_e32 v144, s25, v4
	s_add_i32 s24, s19, 8
	s_add_i32 s26, s19, 12
	s_add_i32 s29, s20, 16
	v_lshlrev_b64 v[136:137], 13, v[136:137]
	v_lshl_add_u64 v[178:179], v[2:3], 0, v[178:179]
	v_lshl_add_u64 v[138:139], v[2:3], 0, v[138:139]
	v_lshlrev_b64 v[182:183], 13, v[144:145]
	v_or_b32_e32 v144, s27, v4
	v_mov_b32_e32 v153, v145
	v_mov_b32_e32 v169, v145
	s_add_i32 s31, s20, 20
; #define LAS __attribute__((address_space(3)))
; template <bool MAPIN>
; __device__ __forceinline__ void transpose_item(const float* W, int K, int N, bf16_t* WT, LAS float* scr, int item, int lane, const float* gk = nullptr) {
;     ...
;     for (int i = 0; i < 32; ++i) { const int kk = 2 * i + (lane >> 5); scr[kk * 33 + (lane & 31)] = W[(size_t)(k0 + kk) * N + n0 + (lane & 31)]; }
;     asm volatile("s_waitcnt lgkmcnt(0)" ::: "memory");
;     const int c = lane & 7;
; #pragma unroll
;     for (int j = 0; j < 4; ++j) { const int n = (lane >> 3) + 8 * j; const LAS float* s = scr + (8 * c) * 33 + n;
;         f32x4 ga = (f32x4){1.f, 1.f, 1.f, 1.f}, gb = ga;
;         if (gk) { ga = *(const f32x4*)(gk + k0 + 8 * c); gb = *(const f32x4*)(gk + k0 + 8 * c + 4); }
	v_or_b32_e32 v152, s24, v5
	v_or_b32_e32 v168, s26, v5
	v_lshl_add_u64 v[136:137], v[2:3], 0, v[136:137]
	v_lshl_add_u64 v[180:181], v[2:3], 0, v[180:181]
	global_load_dword v151, v[178:179], off
	global_load_dword v155, v[136:137], off
	global_load_dword v195, v[180:181], off
	global_load_dword v197, v[138:139], off
	v_lshlrev_b64 v[138:139], 13, v[144:145]
	v_or_b32_e32 v144, s29, v4
	s_add_i32 s28, s19, 16
	s_add_i32 s30, s19, 20
	s_add_i32 s35, s20, 24
	v_lshlrev_b64 v[152:153], 13, v[152:153]
	v_lshlrev_b64 v[168:169], 13, v[168:169]
	v_lshl_add_u64 v[136:137], v[2:3], 0, v[182:183]
	v_lshl_add_u64 v[138:139], v[2:3], 0, v[138:139]
	v_lshlrev_b64 v[178:179], 13, v[144:145]
	v_or_b32_e32 v144, s31, v4
	v_mov_b32_e32 v171, v145
	v_mov_b32_e32 v173, v145
	s_add_i32 s34, s19, 24
	s_add_i32 s76, s19, 28
	s_add_i32 s77, s20, 28
	v_or_b32_e32 v170, s28, v5
	v_or_b32_e32 v172, s30, v5
	v_lshl_add_u64 v[152:153], v[2:3], 0, v[152:153]
	v_lshl_add_u64 v[168:169], v[2:3], 0, v[168:169]
	global_load_dword v198, v[136:137], off
	global_load_dword v199, v[152:153], off
	global_load_dword v200, v[138:139], off
	global_load_dword v201, v[168:169], off
	v_lshlrev_b64 v[138:139], 13, v[144:145]
	v_or_b32_e32 v144, s35, v4
	v_mov_b32_e32 v175, v145
	v_mov_b32_e32 v177, v145
	v_or_b32_e32 v174, s34, v5
	v_or_b32_e32 v176, s76, v5
	v_lshlrev_b64 v[170:171], 13, v[170:171]
	v_lshlrev_b64 v[172:173], 13, v[172:173]
	v_lshl_add_u64 v[136:137], v[2:3], 0, v[178:179]
	v_lshl_add_u64 v[138:139], v[2:3], 0, v[138:139]
	v_lshlrev_b64 v[152:153], 13, v[144:145]
	v_or_b32_e32 v144, s77, v4
	v_lshlrev_b64 v[174:175], 13, v[174:175]
	v_lshlrev_b64 v[176:177], 13, v[176:177]
	v_lshl_add_u64 v[170:171], v[2:3], 0, v[170:171]
	v_lshl_add_u64 v[172:173], v[2:3], 0, v[172:173]
	global_load_dword v202, v[136:137], off
	global_load_dword v203, v[170:171], off
	global_load_dword v204, v[138:139], off
	global_load_dword v205, v[172:173], off
	v_lshl_add_u64 v[136:137], v[2:3], 0, v[152:153]
	v_lshlrev_b64 v[138:139], 13, v[144:145]
	v_lshl_add_u64 v[174:175], v[2:3], 0, v[174:175]
	v_lshl_add_u64 v[176:177], v[2:3], 0, v[176:177]
	v_lshl_add_u64 v[138:139], v[2:3], 0, v[138:139]
	global_load_dword v144, v[136:137], off
	global_load_dword v206, v[174:175], off
	global_load_dword v207, v[138:139], off
	global_load_dword v208, v[176:177], off
	v_or_b32_e32 v138, s19, v13
	v_or_b32_e32 v136, s20, v12
	s_add_i32 s17, s17, 16
	s_add_i32 s16, s16, 16
	s_add_i32 s18, s18, -16
	v_mad_u64_u32 v[136:137], s[20:21], v136, s36, v[16:17]
	v_mad_u64_u32 v[138:139], s[20:21], v138, s36, v[16:17]
	v_or_b32_e32 v137, s22, v13
	v_or_b32_e32 v139, s23, v12
	v_or_b32_e32 v172, s24, v13
	v_or_b32_e32 v170, s25, v12
	v_or_b32_e32 v176, s26, v13
	v_or_b32_e32 v174, s27, v12
	v_or_b32_e32 v180, s28, v13
	v_or_b32_e32 v178, s29, v12
	v_or_b32_e32 v184, s30, v13
	v_or_b32_e32 v182, s31, v12
	v_or_b32_e32 v188, s34, v13
	v_or_b32_e32 v186, s35, v12
	v_or_b32_e32 v192, s76, v13
	v_or_b32_e32 v190, s77, v12
	s_cmp_lg_u32 s18, 0
	v_mad_u64_u32 v[152:153], s[20:21], v139, s36, v[16:17]
	v_mad_u64_u32 v[168:169], s[20:21], v137, s36, v[16:17]
	v_mad_u64_u32 v[170:171], s[20:21], v170, s36, v[16:17]
	v_mad_u64_u32 v[172:173], s[20:21], v172, s36, v[16:17]
	v_mad_u64_u32 v[174:175], s[20:21], v174, s36, v[16:17]
	v_mad_u64_u32 v[176:177], s[20:21], v176, s36, v[16:17]
	v_mad_u64_u32 v[178:179], s[20:21], v178, s36, v[16:17]
	v_mad_u64_u32 v[180:181], s[20:21], v180, s36, v[16:17]
	v_mad_u64_u32 v[182:183], s[20:21], v182, s36, v[16:17]
	v_mad_u64_u32 v[184:185], s[20:21], v184, s36, v[16:17]
	v_mad_u64_u32 v[186:187], s[20:21], v186, s36, v[16:17]
	v_mad_u64_u32 v[188:189], s[20:21], v188, s36, v[16:17]
	v_mad_u64_u32 v[190:191], s[20:21], v190, s36, v[16:17]
	v_mad_u64_u32 v[192:193], s[20:21], v192, s36, v[16:17]
	s_waitcnt vmcnt(0)
	ds_write_b32 v6, v21
	ds_write_b32 v8, v25
	ds_write_b32 v22, v65
	ds_write_b32 v38, v67
	ds_write_b32 v40, v68
	ds_write_b32 v42, v69
	ds_write_b32 v44, v70
	ds_write_b32 v46, v71
	ds_write_b32 v48, v72
	ds_write_b32 v50, v73
	ds_write_b32 v52, v74
	ds_write_b32 v54, v75
	ds_write_b32 v56, v14
	ds_write_b32 v58, v76
	ds_write_b32 v60, v77
	ds_write_b32 v62, v78
	ds_write_b32 v136, v151
	ds_write_b32 v138, v155
	ds_write_b32 v152, v195
	ds_write_b32 v168, v197
	ds_write_b32 v170, v198
	ds_write_b32 v172, v199
	ds_write_b32 v174, v200
	ds_write_b32 v176, v201
	ds_write_b32 v178, v202
	ds_write_b32 v180, v203
	ds_write_b32 v182, v204
	ds_write_b32 v184, v205
	ds_write_b32 v186, v144
	ds_write_b32 v188, v206
	ds_write_b32 v190, v207
	ds_write_b32 v192, v208
	s_waitcnt lgkmcnt(0)
	v_lshlrev_b32_e32 v14, 2, v24
	v_cmp_ne_u64_e32 vcc, 0, v[0:1]
	v_lshl_add_u64 v[0:1], v[0:1], 0, v[14:15]
	v_lshlrev_b32_e32 v14, 2, v18
	v_lshl_add_u64 v[22:23], v[0:1], 0, v[14:15]
	v_mov_b32_e32 v0, 1.0
	v_mov_b32_e32 v6, 1.0
	v_mov_b32_e32 v7, 1.0
	v_mov_b32_e32 v8, 1.0
	v_mov_b32_e32 v9, 1.0
	v_mov_b32_e32 v2, 1.0
	v_mov_b32_e32 v3, 1.0
	v_mov_b32_e32 v4, 1.0
	v_mov_b32_e32 v5, 1.0
	s_and_saveexec_b64 s[16:17], vcc
	s_cbranch_execz .LBB0_111
	global_load_dwordx4 v[6:9], v[22:23], off
	global_load_dwordx4 v[2:5], v[22:23], off offset:16

; template <bool MAPIN>
; __device__ __forceinline__ void transpose_item(const float* W, int K, int N, bf16_t* WT, LAS float* scr, int item, int lane, const float* gk = nullptr) {
;     ...
;     for (int i = 0; i < 32; ++i) { const int kk = 2 * i + (lane >> 5); scr[kk * 33 + (lane & 31)] = W[(size_t)(k0 + kk) * N + n0 + (lane & 31)]; }
.LBB0_120:
	s_lshl_b32 s19, s0, 1
	s_lshl_b32 s20, s1, 1
	v_or_b32_e32 v2, s19, v13
	v_or_b32_e32 v11, s20, v12
	s_add_i32 s21, s19, 4
	s_add_i32 s22, s20, 4
	s_add_i32 s23, s19, 8
	s_add_i32 s24, s20, 8
	s_add_i32 s25, s19, 12
	s_add_i32 s26, s20, 12
	s_add_i32 s27, s19, 16
	s_add_i32 s28, s20, 16
	s_add_i32 s29, s19, 20
	s_add_i32 s30, s20, 20
	s_add_i32 s31, s19, 24
	s_add_i32 s34, s20, 24
	s_add_i32 s19, s19, 28
	s_add_i32 s20, s20, 28
	v_add_u32_e32 v4, v11, v24
	v_or_b32_e32 v14, s21, v13
	v_or_b32_e32 v21, s22, v12
	v_or_b32_e32 v25, s23, v13
	v_or_b32_e32 v62, s24, v12
	v_or_b32_e32 v63, s25, v13
	v_or_b32_e32 v65, s26, v12
	v_or_b32_e32 v67, s27, v13
	v_or_b32_e32 v68, s28, v12
	v_or_b32_e32 v69, s29, v13
	v_or_b32_e32 v70, s30, v12
	v_or_b32_e32 v71, s31, v13
	v_or_b32_e32 v72, s34, v12
	v_or_b32_e32 v73, s19, v13
	v_or_b32_e32 v74, s20, v12
	v_add_u32_e32 v5, v2, v3
	v_mul_lo_u32 v4, v4, s46
	v_add_u32_e32 v9, v14, v3
	v_add_u32_e32 v8, v21, v24
	v_add_u32_e32 v23, v25, v3
	v_add_u32_e32 v38, v62, v24
	v_add_u32_e32 v39, v63, v3
	v_add_u32_e32 v41, v65, v24
	v_add_u32_e32 v43, v67, v3
	v_add_u32_e32 v45, v68, v24
	v_add_u32_e32 v47, v69, v3
	v_add_u32_e32 v49, v70, v24
	v_add_u32_e32 v51, v71, v3
	v_add_u32_e32 v53, v72, v24
	v_add_u32_e32 v55, v73, v3
	v_add_u32_e32 v57, v74, v24
	v_mul_lo_u32 v6, v5, s46
	v_ashrrev_i32_e32 v5, 31, v4
	v_mul_lo_u32 v8, v8, s46
	v_mul_lo_u32 v22, v9, s46
	v_mul_lo_u32 v38, v38, s46
	v_mul_lo_u32 v40, v23, s46
	v_mul_lo_u32 v42, v41, s46
	v_mul_lo_u32 v44, v39, s46
	v_mul_lo_u32 v46, v45, s46
	v_mul_lo_u32 v48, v43, s46
	v_mul_lo_u32 v50, v49, s46
	v_mul_lo_u32 v52, v47, s46
	v_mul_lo_u32 v54, v53, s46
	v_mul_lo_u32 v56, v51, s46
	v_mul_lo_u32 v58, v57, s46
	v_mul_lo_u32 v60, v55, s46
	v_ashrrev_i32_e32 v7, 31, v6
	v_lshl_add_u64 v[4:5], v[0:1], 0, v[4:5]
	v_ashrrev_i32_e32 v23, 31, v22
	v_ashrrev_i32_e32 v9, 31, v8
	v_ashrrev_i32_e32 v41, 31, v40
	v_ashrrev_i32_e32 v39, 31, v38
	v_ashrrev_i32_e32 v45, 31, v44
	v_ashrrev_i32_e32 v43, 31, v42
	v_ashrrev_i32_e32 v49, 31, v48
	v_ashrrev_i32_e32 v47, 31, v46
	v_ashrrev_i32_e32 v53, 31, v52
	v_ashrrev_i32_e32 v51, 31, v50
	v_ashrrev_i32_e32 v57, 31, v56
	v_ashrrev_i32_e32 v55, 31, v54
	v_ashrrev_i32_e32 v61, 31, v60
	v_ashrrev_i32_e32 v59, 31, v58
	v_lshl_add_u64 v[6:7], v[0:1], 0, v[6:7]
	v_lshl_add_u64 v[8:9], v[0:1], 0, v[8:9]
	v_lshl_add_u64 v[22:23], v[0:1], 0, v[22:23]
	v_lshl_add_u64 v[38:39], v[0:1], 0, v[38:39]
	v_lshl_add_u64 v[40:41], v[0:1], 0, v[40:41]
	v_lshl_add_u64 v[42:43], v[0:1], 0, v[42:43]
	v_lshl_add_u64 v[44:45], v[0:1], 0, v[44:45]
	v_lshl_add_u64 v[46:47], v[0:1], 0, v[46:47]
	v_lshl_add_u64 v[48:49], v[0:1], 0, v[48:49]
	v_lshl_add_u64 v[50:51], v[0:1], 0, v[50:51]
	v_lshl_add_u64 v[52:53], v[0:1], 0, v[52:53]
	v_lshl_add_u64 v[54:55], v[0:1], 0, v[54:55]
	v_lshl_add_u64 v[56:57], v[0:1], 0, v[56:57]
	v_lshl_add_u64 v[58:59], v[0:1], 0, v[58:59]
	v_lshl_add_u64 v[60:61], v[0:1], 0, v[60:61]
	global_load_dword v75, v[4:5], off
	global_load_dword v76, v[6:7], off
	global_load_dword v77, v[8:9], off
	global_load_dword v78, v[22:23], off
	global_load_dword v79, v[38:39], off
	global_load_dword v80, v[40:41], off
	global_load_dword v81, v[42:43], off
	global_load_dword v82, v[44:45], off
	global_load_dword v83, v[46:47], off
	global_load_dword v84, v[48:49], off
	global_load_dword v85, v[50:51], off
	global_load_dword v86, v[52:53], off
	global_load_dword v87, v[54:55], off
	global_load_dword v88, v[56:57], off
	global_load_dword v89, v[58:59], off
	global_load_dword v90, v[60:61], off
	s_add_i32 s1, s1, 16
	s_add_i32 s0, s0, 16
	s_add_i32 s18, s18, -16
	v_mad_u64_u32 v[4:5], s[20:21], v11, s36, v[16:17]
	s_cmp_lg_u32 s18, 0
	v_mad_u64_u32 v[6:7], s[20:21], v2, s36, v[16:17]
	v_mad_u64_u32 v[8:9], s[20:21], v21, s36, v[16:17]
	v_mad_u64_u32 v[22:23], s[20:21], v14, s36, v[16:17]
	v_mad_u64_u32 v[38:39], s[20:21], v62, s36, v[16:17]
	v_mad_u64_u32 v[40:41], s[20:21], v25, s36, v[16:17]
	v_mad_u64_u32 v[42:43], s[20:21], v65, s36, v[16:17]
	v_mad_u64_u32 v[44:45], s[20:21], v63, s36, v[16:17]
	v_mad_u64_u32 v[46:47], s[20:21], v68, s36, v[16:17]
	v_mad_u64_u32 v[48:49], s[20:21], v67, s36, v[16:17]
	v_mad_u64_u32 v[50:51], s[20:21], v70, s36, v[16:17]
	v_mad_u64_u32 v[52:53], s[20:21], v69, s36, v[16:17]
	v_mad_u64_u32 v[54:55], s[20:21], v72, s36, v[16:17]
	v_mad_u64_u32 v[56:57], s[20:21], v71, s36, v[16:17]
	v_mad_u64_u32 v[58:59], s[20:21], v74, s36, v[16:17]
	v_mad_u64_u32 v[60:61], s[20:21], v73, s36, v[16:17]
	s_lshl_b32 s19, s0, 1
	s_lshl_b32 s20, s1, 1
	v_or_b32_e32 v132, s19, v13
	v_or_b32_e32 v141, s20, v12
	s_add_i32 s21, s19, 4
	s_add_i32 s22, s20, 4
	s_add_i32 s23, s19, 8
	s_add_i32 s24, s20, 8
	s_add_i32 s25, s19, 12
	s_add_i32 s26, s20, 12
	s_add_i32 s27, s19, 16
	s_add_i32 s28, s20, 16
	s_add_i32 s29, s19, 20
	s_add_i32 s30, s20, 20
	s_add_i32 s31, s19, 24
	s_add_i32 s34, s20, 24
	s_add_i32 s19, s19, 28
	s_add_i32 s20, s20, 28
	v_add_u32_e32 v134, v141, v24
	v_or_b32_e32 v144, s21, v13
	v_or_b32_e32 v151, s22, v12
	v_or_b32_e32 v155, s23, v13
	v_or_b32_e32 v192, s24, v12
	v_or_b32_e32 v193, s25, v13
	v_or_b32_e32 v195, s26, v12
	v_or_b32_e32 v197, s27, v13
	v_or_b32_e32 v198, s28, v12
	v_or_b32_e32 v199, s29, v13
	v_or_b32_e32 v200, s30, v12
	v_or_b32_e32 v201, s31, v13
	v_or_b32_e32 v202, s34, v12
	v_or_b32_e32 v203, s19, v13
	v_or_b32_e32 v204, s20, v12
	v_add_u32_e32 v135, v132, v3
; #define LAS __attribute__((address_space(3)))
; template <bool MAPIN>
; __device__ __forceinline__ void transpose_item(const float* W, int K, int N, bf16_t* WT, LAS float* scr, int item, int lane, const float* gk = nullptr) {
;     ...
;     for (int i = 0; i < 32; ++i) { const int kk = 2 * i + (lane >> 5); scr[kk * 33 + (lane & 31)] = W[(size_t)(k0 + kk) * N + n0 + (lane & 31)]; }
;     asm volatile("s_waitcnt lgkmcnt(0)" ::: "memory");
;     const int c = lane & 7;
; #pragma unroll
;     for (int j = 0; j < 4; ++j) { const int n = (lane >> 3) + 8 * j; const LAS float* s = scr + (8 * c) * 33 + n;
;         f32x4 ga = (f32x4){1.f, 1.f, 1.f, 1.f}, gb = ga;
;         if (gk) { ga = *(const f32x4*)(gk + k0 + 8 * c); gb = *(const f32x4*)(gk + k0 + 8 * c + 4); }
	v_mul_lo_u32 v134, v134, s46
	v_add_u32_e32 v139, v144, v3
	v_add_u32_e32 v138, v151, v24
	v_add_u32_e32 v153, v155, v3
	v_add_u32_e32 v168, v192, v24
	v_add_u32_e32 v169, v193, v3
	v_add_u32_e32 v171, v195, v24
	v_add_u32_e32 v173, v197, v3
	v_add_u32_e32 v175, v198, v24
	v_add_u32_e32 v177, v199, v3
	v_add_u32_e32 v179, v200, v24
	v_add_u32_e32 v181, v201, v3
	v_add_u32_e32 v183, v202, v24
	v_add_u32_e32 v185, v203, v3
	v_add_u32_e32 v187, v204, v24
	v_mul_lo_u32 v136, v135, s46
	v_ashrrev_i32_e32 v135, 31, v134
	v_mul_lo_u32 v138, v138, s46
	v_mul_lo_u32 v152, v139, s46
	v_mul_lo_u32 v168, v168, s46
	v_mul_lo_u32 v170, v153, s46
	v_mul_lo_u32 v172, v171, s46
	v_mul_lo_u32 v174, v169, s46
	v_mul_lo_u32 v176, v175, s46
	v_mul_lo_u32 v178, v173, s46
	v_mul_lo_u32 v180, v179, s46
	v_mul_lo_u32 v182, v177, s46
	v_mul_lo_u32 v184, v183, s46
	v_mul_lo_u32 v186, v181, s46
	v_mul_lo_u32 v188, v187, s46
	v_mul_lo_u32 v190, v185, s46
	v_ashrrev_i32_e32 v137, 31, v136
	v_lshl_add_u64 v[134:135], v[0:1], 0, v[134:135]
	v_ashrrev_i32_e32 v153, 31, v152
	v_ashrrev_i32_e32 v139, 31, v138
	v_ashrrev_i32_e32 v171, 31, v170
	v_ashrrev_i32_e32 v169, 31, v168
	v_ashrrev_i32_e32 v175, 31, v174
	v_ashrrev_i32_e32 v173, 31, v172
	v_ashrrev_i32_e32 v179, 31, v178
	v_ashrrev_i32_e32 v177, 31, v176
	v_ashrrev_i32_e32 v183, 31, v182
	v_ashrrev_i32_e32 v181, 31, v180
	v_ashrrev_i32_e32 v187, 31, v186
	v_ashrrev_i32_e32 v185, 31, v184
	v_ashrrev_i32_e32 v191, 31, v190
	v_ashrrev_i32_e32 v189, 31, v188
	v_lshl_add_u64 v[136:137], v[0:1], 0, v[136:137]
	v_lshl_add_u64 v[138:139], v[0:1], 0, v[138:139]
	v_lshl_add_u64 v[152:153], v[0:1], 0, v[152:153]
	v_lshl_add_u64 v[168:169], v[0:1], 0, v[168:169]
	v_lshl_add_u64 v[170:171], v[0:1], 0, v[170:171]
	v_lshl_add_u64 v[172:173], v[0:1], 0, v[172:173]
	v_lshl_add_u64 v[174:175], v[0:1], 0, v[174:175]
	v_lshl_add_u64 v[176:177], v[0:1], 0, v[176:177]
	v_lshl_add_u64 v[178:179], v[0:1], 0, v[178:179]
	v_lshl_add_u64 v[180:181], v[0:1], 0, v[180:181]
	v_lshl_add_u64 v[182:183], v[0:1], 0, v[182:183]
	v_lshl_add_u64 v[184:185], v[0:1], 0, v[184:185]
	v_lshl_add_u64 v[186:187], v[0:1], 0, v[186:187]
	v_lshl_add_u64 v[188:189], v[0:1], 0, v[188:189]
	v_lshl_add_u64 v[190:191], v[0:1], 0, v[190:191]
	global_load_dword v205, v[134:135], off
	global_load_dword v206, v[136:137], off
	global_load_dword v207, v[138:139], off
	global_load_dword v208, v[152:153], off
	global_load_dword v209, v[168:169], off
	global_load_dword v210, v[170:171], off
	global_load_dword v211, v[172:173], off
	global_load_dword v212, v[174:175], off
	global_load_dword v213, v[176:177], off
	global_load_dword v214, v[178:179], off
	global_load_dword v215, v[180:181], off
	global_load_dword v216, v[182:183], off
	global_load_dword v217, v[184:185], off
	global_load_dword v218, v[186:187], off
	global_load_dword v219, v[188:189], off
	global_load_dword v220, v[190:191], off
	s_add_i32 s1, s1, 16
	s_add_i32 s0, s0, 16
	s_add_i32 s18, s18, -16
	v_mad_u64_u32 v[134:135], s[20:21], v141, s36, v[16:17]
	s_cmp_lg_u32 s18, 0
	v_mad_u64_u32 v[136:137], s[20:21], v132, s36, v[16:17]
	v_mad_u64_u32 v[138:139], s[20:21], v151, s36, v[16:17]
	v_mad_u64_u32 v[152:153], s[20:21], v144, s36, v[16:17]
	v_mad_u64_u32 v[168:169], s[20:21], v192, s36, v[16:17]
	v_mad_u64_u32 v[170:171], s[20:21], v155, s36, v[16:17]
	v_mad_u64_u32 v[172:173], s[20:21], v195, s36, v[16:17]
	v_mad_u64_u32 v[174:175], s[20:21], v193, s36, v[16:17]
	v_mad_u64_u32 v[176:177], s[20:21], v198, s36, v[16:17]
	v_mad_u64_u32 v[178:179], s[20:21], v197, s36, v[16:17]
	v_mad_u64_u32 v[180:181], s[20:21], v200, s36, v[16:17]
	v_mad_u64_u32 v[182:183], s[20:21], v199, s36, v[16:17]
	v_mad_u64_u32 v[184:185], s[20:21], v202, s36, v[16:17]
	v_mad_u64_u32 v[186:187], s[20:21], v201, s36, v[16:17]
	v_mad_u64_u32 v[188:189], s[20:21], v204, s36, v[16:17]
	v_mad_u64_u32 v[190:191], s[20:21], v203, s36, v[16:17]
	s_waitcnt vmcnt(0)
	ds_write_b32 v4, v75
	ds_write_b32 v6, v76
	ds_write_b32 v8, v77
	ds_write_b32 v22, v78
	ds_write_b32 v38, v79
	ds_write_b32 v40, v80
	ds_write_b32 v42, v81
	ds_write_b32 v44, v82
	ds_write_b32 v46, v83
	ds_write_b32 v48, v84
	ds_write_b32 v50, v85
	ds_write_b32 v52, v86
	ds_write_b32 v54, v87
	ds_write_b32 v56, v88
	ds_write_b32 v58, v89
	ds_write_b32 v60, v90
	ds_write_b32 v134, v205
	ds_write_b32 v136, v206
	ds_write_b32 v138, v207
	ds_write_b32 v152, v208
	ds_write_b32 v168, v209
	ds_write_b32 v170, v210
	ds_write_b32 v172, v211
	ds_write_b32 v174, v212
	ds_write_b32 v176, v213
	ds_write_b32 v178, v214
	ds_write_b32 v180, v215
	ds_write_b32 v182, v216
	ds_write_b32 v184, v217
	ds_write_b32 v186, v218
	ds_write_b32 v188, v219
	ds_write_b32 v190, v220
	v_add_u32_e32 v0, 0xffffc400, v36
	v_cmp_lt_u32_e32 vcc, s47, v0
	v_mov_b32_e32 v1, s40
	v_cmp_gt_u32_e64 s[0:1], s48, v0
	v_mov_b32_e32 v0, s39
	s_waitcnt lgkmcnt(0)
	v_ashrrev_i32_e32 v25, 31, v24
	v_cndmask_b32_e64 v1, v1, 0, s[0:1]
	v_cndmask_b32_e64 v0, v0, 0, s[0:1]
	v_lshl_add_u64 v[0:1], v[24:25], 2, v[0:1]
	v_lshlrev_b32_e32 v14, 2, v18
	v_lshl_add_u64 v[22:23], v[0:1], 0, v[14:15]
	v_mov_b32_e32 v6, 1.0
	v_mov_b32_e32 v7, 1.0
	v_mov_b32_e32 v8, 1.0
	v_mov_b32_e32 v9, 1.0
	v_mov_b32_e32 v2, 1.0
	v_mov_b32_e32 v3, 1.0
	v_mov_b32_e32 v4, 1.0
	v_mov_b32_e32 v5, 1.0
	s_and_saveexec_b64 s[0:1], vcc
	s_cbranch_execz .LBB0_123
	global_load_dwordx4 v[6:9], v[22:23], off
	global_load_dwordx4 v[2:5], v[22:23], off offset:16

; #define PG8_STAGE(bufoff, gbase, voff) do { _Pragma("unroll") for (int _i = 0; _i < 2; ++_i) \
;         __builtin_amdgcn_global_load_lds((const unsigned*)((const char*)(gbase) + (voff)[_i]), (PG8_LAS unsigned*)(lds + (bufoff) + ldsw + _i * 8192), 16, 0, 0); } while (0)
; #define PG8_LDA(dst, b, h) do { _Pragma("unroll") for (int m = 0; m < 4; ++m) _Pragma("unroll") for (int k = 0; k < 2; ++k) dst[m][k] = *(const PG8_LAS bf16x8*)(lds + PG8_SA(b, h) + aoff + m * 2048 + k * 1024); } while (0)
; #define PG8_LDB(dst, b, h) do { _Pragma("unroll") for (int n = 0; n < 2; ++n) _Pragma("unroll") for (int k = 0; k < 2; ++k) dst[n][k] = *(const PG8_LAS bf16x8*)(lds + PG8_SB(b, h) + boff + n * 2048 + k * 1024); } while (0)
; #define PG8_MMA(ai, bj, At, Bt) do { __builtin_amdgcn_s_setprio(1); _Pragma("unroll") for (int m = 0; m < 4; ++m) _Pragma("unroll") for (int n = 0; n < 2; ++n) _Pragma("unroll") for (int k = 0; k < 2; ++k) \
;         acc[ai][bj][m][n] = __builtin_amdgcn_mfma_f32_16x16x32_bf16(Bt[n][k], At[m][k], acc[ai][bj][m][n], 0, 0, 0); __builtin_amdgcn_s_setprio(0); } while (0)
; #define PG8_WAIT_V(n) asm volatile("s_waitcnt vmcnt(" #n ")" ::: "memory")
; #define PG8_WAIT_L(n) asm volatile("s_waitcnt lgkmcnt(" #n ")" ::: "memory")
; #define PG8_BAR __builtin_amdgcn_s_barrier()
; #define PG8_SCHED __builtin_amdgcn_sched_barrier(0)
; template <class Epi, class Sched, bool ALIGN_EPI = false, bool SP2 = true>
; __device__ __forceinline__ void gemm_phase(PG8_LAS unsigned char* lds, const Gemm g, const Sched& S, const Epi& E, int wave_s) {
;     ...
;             PG8_LDB(B0, 0, 0); PG8_LDB(B1, 0, 1); PG8_SCHED; PG8_LDA(At, 0, 0); PG8_STAGE(PG8_SA(1, 1), a1 + hstepA, voffA);
;             PG8_WAIT_V(8); PG8_WAIT_L(0); PG8_BAR; PG8_MMA(0, 0, At, B0); PG8_MMA(0, 1, At, B1); PG8_BAR; PG8_SCHED;
;     ...
; #pragma unroll
;         for (int a = 0; a < 2; ++a)
; #pragma unroll
;             for (int b = 0; b < 2; ++b)
; #pragma unroll
;                 for (int m = 0; m < 4; ++m)
; #pragma unroll
;                     for (int n = 0; n < 2; ++n) acc[a][b][m][n] = (f32x4){0.f, 0.f, 0.f, 0.f};
;         cur = nxt; cA = nA; cB = nB; ++ui;
.LBB0_607:
	s_ashr_i32 s19, s18, 31
	s_lshl_b64 s[22:23], s[18:19], 20
	s_add_u32 s22, s30, s22
	s_addc_u32 s23, s31, s23
	s_and_b64 s[6:7], s[6:7], exec
	s_cselect_b32 s19, s23, s27
	s_cselect_b32 s33, s22, s26
	s_add_u32 s72, s26, 0x100
	v_mov_b32_e32 v2, 0
	s_addc_u32 s73, s27, 0
	s_mov_b32 s74, -2
	v_mov_b32_e32 v3, v2
	v_mov_b32_e32 v4, v2
	v_mov_b32_e32 v5, v2
	v_mov_b32_e32 v6, v2
	v_mov_b32_e32 v7, v2
	v_mov_b32_e32 v8, v2
	v_mov_b32_e32 v9, v2
	v_mov_b32_e32 v18, v2
	v_mov_b32_e32 v19, v2
	v_mov_b32_e32 v20, v2
	v_mov_b32_e32 v21, v2
	v_mov_b32_e32 v22, v2
	v_mov_b32_e32 v23, v2
	v_mov_b32_e32 v24, v2
	v_mov_b32_e32 v25, v2
	v_mov_b32_e32 v34, v2
	v_mov_b32_e32 v35, v2
	v_mov_b32_e32 v36, v2
	v_mov_b32_e32 v37, v2
	v_mov_b32_e32 v38, v2
	v_mov_b32_e32 v39, v2
	v_mov_b32_e32 v40, v2
	v_mov_b32_e32 v41, v2
	v_mov_b32_e32 v50, v2
	v_mov_b32_e32 v51, v2
	v_mov_b32_e32 v52, v2
	v_mov_b32_e32 v53, v2
	v_mov_b32_e32 v54, v2
	v_mov_b32_e32 v55, v2
	v_mov_b32_e32 v56, v2
	v_mov_b32_e32 v57, v2
	v_mov_b32_e32 v10, v2
	v_mov_b32_e32 v11, v2
	v_mov_b32_e32 v12, v2
	v_mov_b32_e32 v13, v2
	v_mov_b32_e32 v14, v2
	v_mov_b32_e32 v15, v2
	v_mov_b32_e32 v16, v2
	v_mov_b32_e32 v17, v2
	v_mov_b32_e32 v26, v2
	v_mov_b32_e32 v27, v2
	v_mov_b32_e32 v28, v2
	v_mov_b32_e32 v29, v2
	v_mov_b32_e32 v30, v2
	v_mov_b32_e32 v31, v2
	v_mov_b32_e32 v32, v2
	v_mov_b32_e32 v33, v2
	v_mov_b32_e32 v42, v2
	v_mov_b32_e32 v43, v2
	v_mov_b32_e32 v44, v2
	v_mov_b32_e32 v45, v2
	v_mov_b32_e32 v46, v2
	v_mov_b32_e32 v47, v2
	v_mov_b32_e32 v48, v2
	v_mov_b32_e32 v49, v2
	v_mov_b32_e32 v58, v2
	v_mov_b32_e32 v59, v2
	v_mov_b32_e32 v60, v2
	v_mov_b32_e32 v61, v2
	v_mov_b32_e32 v62, v2
	v_mov_b32_e32 v63, v2
	v_mov_b32_e32 v64, v2
	v_mov_b32_e32 v65, v2
	v_mov_b32_e32 v66, v2
	v_mov_b32_e32 v67, v2
	v_mov_b32_e32 v68, v2
	v_mov_b32_e32 v69, v2
	v_mov_b32_e32 v70, v2
	v_mov_b32_e32 v71, v2
	v_mov_b32_e32 v72, v2
	v_mov_b32_e32 v73, v2
	v_mov_b32_e32 v82, v2
	v_mov_b32_e32 v83, v2
	v_mov_b32_e32 v84, v2
	v_mov_b32_e32 v85, v2
	v_mov_b32_e32 v86, v2
	v_mov_b32_e32 v87, v2
	v_mov_b32_e32 v88, v2
	v_mov_b32_e32 v89, v2
	v_mov_b32_e32 v98, v2
	v_mov_b32_e32 v99, v2
	v_mov_b32_e32 v100, v2
	v_mov_b32_e32 v101, v2
	v_mov_b32_e32 v102, v2
	v_mov_b32_e32 v103, v2
	v_mov_b32_e32 v104, v2
	v_mov_b32_e32 v105, v2
	v_mov_b32_e32 v114, v2
	v_mov_b32_e32 v115, v2
	v_mov_b32_e32 v116, v2
	v_mov_b32_e32 v117, v2
	v_mov_b32_e32 v118, v2
	v_mov_b32_e32 v119, v2
	v_mov_b32_e32 v120, v2
	v_mov_b32_e32 v121, v2
	v_mov_b32_e32 v74, v2
	v_mov_b32_e32 v75, v2
	v_mov_b32_e32 v76, v2
	v_mov_b32_e32 v77, v2
	v_mov_b32_e32 v78, v2
	v_mov_b32_e32 v79, v2
	v_mov_b32_e32 v80, v2
	v_mov_b32_e32 v81, v2
	v_mov_b32_e32 v90, v2
	v_mov_b32_e32 v91, v2
	v_mov_b32_e32 v92, v2
	v_mov_b32_e32 v93, v2
	v_mov_b32_e32 v94, v2
	v_mov_b32_e32 v95, v2
	v_mov_b32_e32 v96, v2
	v_mov_b32_e32 v97, v2
	v_mov_b32_e32 v106, v2
	v_mov_b32_e32 v107, v2
	v_mov_b32_e32 v108, v2
	v_mov_b32_e32 v109, v2
	v_mov_b32_e32 v110, v2
	v_mov_b32_e32 v111, v2
	v_mov_b32_e32 v112, v2
	v_mov_b32_e32 v113, v2
	v_mov_b32_e32 v122, v2
	v_mov_b32_e32 v123, v2
	v_mov_b32_e32 v124, v2
	v_mov_b32_e32 v125, v2
	v_mov_b32_e32 v126, v2
	v_mov_b32_e32 v127, v2
	v_mov_b32_e32 v128, v2
	v_mov_b32_e32 v129, v2
	s_cmp_eq_u32 s92, 0
	s_cbranch_scc0 .Lrf_setup_m1
	s_cmp_lt_u32 s3, 64
	s_cselect_b32 s94, s52, s54
	s_cselect_b32 s95, s53, s55
	s_and_b32 s77, s3, 63
	s_lshl_b32 s77, s77, 21
	s_lshl_b32 s32, s0, 10
	s_add_u32 s77, s77, s32
	s_add_u32 s94, s94, s77
	s_addc_u32 s95, s95, 0
	v_lshlrev_b32_e32 v250, 13, v1
	v_lshl_add_u32 v250, v173, 2, v250
	s_branch .Lrf_setup_done
.Lrf_setup_m1:
	s_lshl_b32 s77, s3, 20
	s_lshl_b32 s32, s0, 9
	s_add_u32 s77, s77, s32
	s_add_u32 s94, s58, s77
	s_addc_u32 s95, s59, 0
	v_lshlrev_b32_e32 v250, 12, v1
	v_lshl_add_u32 v250, v173, 1, v250
.Lrf_setup_done:
	s_and_b32 s77, s1, 1
	s_lshl_b32 s77, s77, 10
	v_add_u32_e32 v252, s77, v171
.LBB0_608:
	s_add_u32 s6, s24, 0x100
	s_addc_u32 s7, s25, 0
	s_add_i32 s75, 0, 0x10000
	s_cmp_eq_u32 s74, 28
	s_cselect_b32 s29, s21, s7
	s_cselect_b32 s28, s20, s6
	v_add_u32_e32 v146, s75, v170
	s_cselect_b32 s27, s19, s73
	s_cselect_b32 s26, s33, s72
	s_add_i32 s76, 0, 0x14000
	ds_read_b128 v[130:133], v146
	ds_read_b128 v[134:137], v146 offset:1024
	ds_read_b128 v[158:161], v146 offset:2048
	ds_read_b128 v[162:165], v146 offset:3072
	v_add_u32_e32 v146, s76, v170
	ds_read_b128 v[166:169], v146
	ds_read_b128 v[176:179], v146 offset:1024
	ds_read_b128 v[180:183], v146 offset:2048
	ds_read_b128 v[184:187], v146 offset:3072
	v_lshl_add_u64 v[146:147], s[24:25], 0, v[156:157]
	s_add_i32 m0, s35, 0xc000
	ds_read_b128 v[188:191], v174
	ds_read_b128 v[192:195], v174 offset:1024
	ds_read_b128 v[196:199], v174 offset:2048
	ds_read_b128 v[200:203], v174 offset:3072
	ds_read_b128 v[204:207], v174 offset:4096
	ds_read_b128 v[208:211], v174 offset:5120
	ds_read_b128 v[212:215], v174 offset:6144
	ds_read_b128 v[216:219], v174 offset:7168
	global_load_lds_dwordx4 v[146:147], off
	v_lshl_add_u64 v[146:147], s[24:25], 0, v[154:155]
	s_add_i32 m0, s35, 0xe000
	s_nop 0
	global_load_lds_dwordx4 v[146:147], off
	s_waitcnt vmcnt(8)
	s_waitcnt lgkmcnt(0)
	s_barrier
; #define GAS __attribute__((address_space(1)))
; __device__ __forceinline__ float bf_lo(unsigned w) { return __uint_as_float(w << 16); }
; __device__ __forceinline__ float bf_hi(unsigned w) { return __uint_as_float(w & 0xffff0000u); }
; #define PG8_STAGE(bufoff, gbase, voff) do { _Pragma("unroll") for (int _i = 0; _i < 2; ++_i) \
;         __builtin_amdgcn_global_load_lds((const unsigned*)((const char*)(gbase) + (voff)[_i]), (PG8_LAS unsigned*)(lds + (bufoff) + ldsw + _i * 8192), 16, 0, 0); } while (0)
; #define PG8_LDA(dst, b, h) do { _Pragma("unroll") for (int m = 0; m < 4; ++m) _Pragma("unroll") for (int k = 0; k < 2; ++k) dst[m][k] = *(const PG8_LAS bf16x8*)(lds + PG8_SA(b, h) + aoff + m * 2048 + k * 1024); } while (0)
; #define PG8_MMA(ai, bj, At, Bt) do { __builtin_amdgcn_s_setprio(1); _Pragma("unroll") for (int m = 0; m < 4; ++m) _Pragma("unroll") for (int n = 0; n < 2; ++n) _Pragma("unroll") for (int k = 0; k < 2; ++k) \
;         acc[ai][bj][m][n] = __builtin_amdgcn_mfma_f32_16x16x32_bf16(Bt[n][k], At[m][k], acc[ai][bj][m][n], 0, 0, 0); __builtin_amdgcn_s_setprio(0); } while (0)
; #define PG8_WAIT_V(n) asm volatile("s_waitcnt vmcnt(" #n ")" ::: "memory")
; #define PG8_WAIT_L(n) asm volatile("s_waitcnt lgkmcnt(" #n ")" ::: "memory")
; #define PG8_BAR __builtin_amdgcn_s_barrier()
;     __device__ __forceinline__ void operator()(const f32x4 (&acc)[2][2][4][2], const Unit& u, int wr, int wc, int fr, int fq, const PG8_LAS float* tab) const {
;     ...
;                     if (mode == 0) { a0 = *(const GAS f32x4*)(xo + col0); a1 = *(const GAS f32x4*)(xo + col0 + 4); }
;                     else { const u32x4 w = *(const GAS u32x4*)(xr + col0);
;                         a0 = (f32x4){bf_lo(w.x), bf_hi(w.x), bf_lo(w.y), bf_hi(w.y)}; a1 = (f32x4){bf_lo(w.z), bf_hi(w.z), bf_lo(w.w), bf_hi(w.w)}; }
;                     const f32x4 v0 = a0 + acc[ai][bj][m][0] * ra, v1 = a1 + acc[ai][bj][m][1] * ra;
; template <class Epi, class Sched, bool ALIGN_EPI = false, bool SP2 = true>
; __device__ __forceinline__ void gemm_phase(PG8_LAS unsigned char* lds, const Gemm g, const Sched& S, const Epi& E, int wave_s) {
;     ...
;             PG8_WAIT_V(8); PG8_WAIT_L(0); PG8_BAR; PG8_MMA(0, 0, At, B0); PG8_MMA(0, 1, At, B1); PG8_BAR; PG8_SCHED;
;             PG8_LDA(At, 0, 1); PG8_STAGE(PG8_SB(0, 0), b2, voffB); PG8_STAGE(PG8_SB(0, 1), b2 + hstepB, voffB); PG8_STAGE(PG8_SA(0, 0), a2, voffA);
	s_setprio 1
	s_waitcnt lgkmcnt(0)
	v_mfma_f32_16x16x32_bf16 v[126:129], v[130:133], v[188:191], v[126:129]
	v_mfma_f32_16x16x32_bf16 v[122:125], v[158:161], v[188:191], v[122:125]
	v_mfma_f32_16x16x32_bf16 v[110:113], v[130:133], v[196:199], v[110:113]
	v_mfma_f32_16x16x32_bf16 v[106:109], v[158:161], v[196:199], v[106:109]
	v_mfma_f32_16x16x32_bf16 v[94:97], v[130:133], v[204:207], v[94:97]
	v_mfma_f32_16x16x32_bf16 v[90:93], v[158:161], v[204:207], v[90:93]
	v_mfma_f32_16x16x32_bf16 v[78:81], v[130:133], v[212:215], v[78:81]
	v_mfma_f32_16x16x32_bf16 v[74:77], v[158:161], v[212:215], v[74:77]
	v_mfma_f32_16x16x32_bf16 v[126:129], v[134:137], v[192:195], v[126:129]
	v_mfma_f32_16x16x32_bf16 v[122:125], v[162:165], v[192:195], v[122:125]
	v_mfma_f32_16x16x32_bf16 v[110:113], v[134:137], v[200:203], v[110:113]
	v_mfma_f32_16x16x32_bf16 v[106:109], v[162:165], v[200:203], v[106:109]
	v_mfma_f32_16x16x32_bf16 v[94:97], v[134:137], v[208:211], v[94:97]
	v_mfma_f32_16x16x32_bf16 v[90:93], v[162:165], v[208:211], v[90:93]
	v_mfma_f32_16x16x32_bf16 v[78:81], v[134:137], v[216:219], v[78:81]
	v_mfma_f32_16x16x32_bf16 v[74:77], v[162:165], v[216:219], v[74:77]
	s_setprio 0
	s_setprio 1
	v_mfma_f32_16x16x32_bf16 v[118:121], v[166:169], v[188:191], v[118:121]
	v_mfma_f32_16x16x32_bf16 v[114:117], v[180:183], v[188:191], v[114:117]
	v_mfma_f32_16x16x32_bf16 v[102:105], v[166:169], v[196:199], v[102:105]
	v_mfma_f32_16x16x32_bf16 v[98:101], v[180:183], v[196:199], v[98:101]
	v_mfma_f32_16x16x32_bf16 v[86:89], v[166:169], v[204:207], v[86:89]
	v_mfma_f32_16x16x32_bf16 v[82:85], v[180:183], v[204:207], v[82:85]
	v_mfma_f32_16x16x32_bf16 v[70:73], v[166:169], v[212:215], v[70:73]
	v_mfma_f32_16x16x32_bf16 v[66:69], v[180:183], v[212:215], v[66:69]
	v_mfma_f32_16x16x32_bf16 v[118:121], v[176:179], v[192:195], v[118:121]
	v_mfma_f32_16x16x32_bf16 v[114:117], v[184:187], v[192:195], v[114:117]
	v_mfma_f32_16x16x32_bf16 v[102:105], v[176:179], v[200:203], v[102:105]
	v_mfma_f32_16x16x32_bf16 v[98:101], v[184:187], v[200:203], v[98:101]
	v_mfma_f32_16x16x32_bf16 v[86:89], v[176:179], v[208:211], v[86:89]
	v_mfma_f32_16x16x32_bf16 v[82:85], v[184:187], v[208:211], v[82:85]
	v_mfma_f32_16x16x32_bf16 v[70:73], v[176:179], v[216:219], v[70:73]
	v_mfma_f32_16x16x32_bf16 v[66:69], v[184:187], v[216:219], v[66:69]
	s_setprio 0
	s_barrier
	s_add_i32 s24, s75, s34
	v_lshl_add_u64 v[146:147], s[26:27], 0, v[142:143]
	s_mov_b32 m0, s24
	ds_read_b128 v[188:191], v174 offset:16384
	ds_read_b128 v[192:195], v174 offset:17408
	ds_read_b128 v[196:199], v174 offset:18432
	ds_read_b128 v[200:203], v174 offset:19456
	ds_read_b128 v[204:207], v174 offset:20480
	ds_read_b128 v[208:211], v174 offset:21504
	ds_read_b128 v[212:215], v174 offset:22528
	ds_read_b128 v[216:219], v174 offset:23552
	global_load_lds_dwordx4 v[146:147], off
	s_add_i32 m0, s24, 0x2000
	s_add_u32 s24, s26, 0x80000
	v_lshl_add_u64 v[220:221], s[26:27], 0, v[138:139]
	s_addc_u32 s25, s27, 0
	s_add_i32 s75, s76, s34
	global_load_lds_dwordx4 v[220:221], off
	v_lshl_add_u64 v[222:223], s[24:25], 0, v[142:143]
	s_mov_b32 m0, s75
	v_lshl_add_u64 v[224:225], s[28:29], 0, v[140:141]
	global_load_lds_dwordx4 v[222:223], off
	v_lshl_add_u64 v[222:223], s[24:25], 0, v[138:139]
	s_add_i32 m0, s75, 0x2000
	s_nop 0
	global_load_lds_dwordx4 v[222:223], off
	v_lshl_add_u64 v[222:223], s[28:29], 0, v[144:145]
	s_mov_b32 m0, s35
	s_nop 0
	global_load_lds_dwordx4 v[222:223], off
	s_mov_b32 m0, s37
	s_nop 0
	global_load_lds_dwordx4 v[224:225], off
	s_cmp_lt_i32 s74, 0
	s_cbranch_scc1 .Lrf_join
	s_cmp_eq_u32 s92, 0
	s_cbranch_scc1 .Lrf_tree
	v_lshlrev_b32_e32 v240, 16, v228
	v_and_b32_e32 v241, 0xffff0000, v228
	v_lshlrev_b32_e32 v242, 16, v229
	v_and_b32_e32 v243, 0xffff0000, v229
	v_lshlrev_b32_e32 v244, 16, v230
	v_and_b32_e32 v245, 0xffff0000, v230
	v_lshlrev_b32_e32 v246, 16, v231
	v_and_b32_e32 v247, 0xffff0000, v231
.Lrf_tree:
	s_cmp_ge_u32 s74, 14
	s_cbranch_scc1 .Lrf_t7_15
	s_cmp_ge_u32 s74, 6
	s_cbranch_scc1 .Lrf_t3_7
	s_cmp_ge_u32 s74, 2
	s_cbranch_scc1 .Lrf_t1_3
	v_fmac_f32_e32 v126, v240, v248
	v_fmac_f32_e32 v127, v241, v248
	v_fmac_f32_e32 v128, v242, v248
	v_fmac_f32_e32 v129, v243, v248
	v_fmac_f32_e32 v122, v244, v248
	v_fmac_f32_e32 v123, v245, v248
	v_fmac_f32_e32 v124, v246, v248
	v_fmac_f32_e32 v125, v247, v248
	s_branch .Lrf_join
.Lrf_t1_3:
	s_cmp_ge_u32 s74, 4
	s_cbranch_scc1 .Lrf_t2_3
	v_fmac_f32_e32 v118, v240, v248
	v_fmac_f32_e32 v119, v241, v248
	v_fmac_f32_e32 v120, v242, v248
	v_fmac_f32_e32 v121, v243, v248
	v_fmac_f32_e32 v114, v244, v248
	v_fmac_f32_e32 v115, v245, v248
	v_fmac_f32_e32 v116, v246, v248
	v_fmac_f32_e32 v117, v247, v248
	s_branch .Lrf_join
.Lrf_t2_3:
	v_fmac_f32_e32 v110, v240, v248
	v_fmac_f32_e32 v111, v241, v248
	v_fmac_f32_e32 v112, v242, v248
	v_fmac_f32_e32 v113, v243, v248
	v_fmac_f32_e32 v106, v244, v248
	v_fmac_f32_e32 v107, v245, v248
	v_fmac_f32_e32 v108, v246, v248
	v_fmac_f32_e32 v109, v247, v248
	s_branch .Lrf_join
.Lrf_t3_7:
	s_cmp_ge_u32 s74, 10
	s_cbranch_scc1 .Lrf_t5_7
	s_cmp_ge_u32 s74, 8
	s_cbranch_scc1 .Lrf_t4_5
	v_fmac_f32_e32 v102, v240, v248
	v_fmac_f32_e32 v103, v241, v248
	v_fmac_f32_e32 v104, v242, v248
	v_fmac_f32_e32 v105, v243, v248
	v_fmac_f32_e32 v98, v244, v248
	v_fmac_f32_e32 v99, v245, v248
	v_fmac_f32_e32 v100, v246, v248
	v_fmac_f32_e32 v101, v247, v248
	s_branch .Lrf_join
.Lrf_t4_5:
	v_fmac_f32_e32 v94, v240, v248
	v_fmac_f32_e32 v95, v241, v248
	v_fmac_f32_e32 v96, v242, v248
	v_fmac_f32_e32 v97, v243, v248
	v_fmac_f32_e32 v90, v244, v248
	v_fmac_f32_e32 v91, v245, v248
	v_fmac_f32_e32 v92, v246, v248
	v_fmac_f32_e32 v93, v247, v248
	s_branch .Lrf_join
; #define GAS __attribute__((address_space(1)))
; __device__ __forceinline__ float bf_lo(unsigned w) { return __uint_as_float(w << 16); }
; __device__ __forceinline__ float bf_hi(unsigned w) { return __uint_as_float(w & 0xffff0000u); }
; #define PG8_STAGE(bufoff, gbase, voff) do { _Pragma("unroll") for (int _i = 0; _i < 2; ++_i) \
;         __builtin_amdgcn_global_load_lds((const unsigned*)((const char*)(gbase) + (voff)[_i]), (PG8_LAS unsigned*)(lds + (bufoff) + ldsw + _i * 8192), 16, 0, 0); } while (0)
; #define PG8_LDA(dst, b, h) do { _Pragma("unroll") for (int m = 0; m < 4; ++m) _Pragma("unroll") for (int k = 0; k < 2; ++k) dst[m][k] = *(const PG8_LAS bf16x8*)(lds + PG8_SA(b, h) + aoff + m * 2048 + k * 1024); } while (0)
; #define PG8_LDB(dst, b, h) do { _Pragma("unroll") for (int n = 0; n < 2; ++n) _Pragma("unroll") for (int k = 0; k < 2; ++k) dst[n][k] = *(const PG8_LAS bf16x8*)(lds + PG8_SB(b, h) + boff + n * 2048 + k * 1024); } while (0)
; #define PG8_WAIT_V(n) asm volatile("s_waitcnt vmcnt(" #n ")" ::: "memory")
;     __device__ __forceinline__ void operator()(const f32x4 (&acc)[2][2][4][2], const Unit& u, int wr, int wc, int fr, int fq, const PG8_LAS float* tab) const {
;     ...
;                     if (mode == 0) { a0 = *(const GAS f32x4*)(xo + col0); a1 = *(const GAS f32x4*)(xo + col0 + 4); }
;                     else { const u32x4 w = *(const GAS u32x4*)(xr + col0);
;                         a0 = (f32x4){bf_lo(w.x), bf_hi(w.x), bf_lo(w.y), bf_hi(w.y)}; a1 = (f32x4){bf_lo(w.z), bf_hi(w.z), bf_lo(w.w), bf_hi(w.w)}; }
;                     const f32x4 v0 = a0 + acc[ai][bj][m][0] * ra, v1 = a1 + acc[ai][bj][m][1] * ra;
; template <class Epi, class Sched, bool ALIGN_EPI = false, bool SP2 = true>
; __device__ __forceinline__ void gemm_phase(PG8_LAS unsigned char* lds, const Gemm g, const Sched& S, const Epi& E, int wave_s) {
;     ...
;             PG8_WAIT_V(8); PG8_WAIT_L(0); PG8_BAR; PG8_MMA(1, 0, At, B0); PG8_MMA(1, 1, At, B1); PG8_BAR; PG8_SCHED;
;             PG8_LDB(B0, 1, 0); PG8_LDB(B1, 1, 1); PG8_SCHED; PG8_LDA(At, 1, 0); PG8_STAGE(PG8_SA(0, 1), a2 + hstepA, voffA);
;             PG8_WAIT_V(8); PG8_WAIT_L(0); PG8_BAR; PG8_MMA(0, 0, At, B0); PG8_MMA(0, 1, At, B1); PG8_BAR; PG8_SCHED;
;             PG8_LDA(At, 1, 1); PG8_STAGE(PG8_SB(1, 0), b3, voffB); PG8_STAGE(PG8_SB(1, 1), b3 + hstepB, voffB); PG8_STAGE(PG8_SA(1, 0), a3, voffA);
.Lrf_t5_7:
	s_cmp_ge_u32 s74, 12
	s_cbranch_scc1 .Lrf_t6_7
	v_fmac_f32_e32 v86, v240, v248
	v_fmac_f32_e32 v87, v241, v248
	v_fmac_f32_e32 v88, v242, v248
	v_fmac_f32_e32 v89, v243, v248
	v_fmac_f32_e32 v82, v244, v248
	v_fmac_f32_e32 v83, v245, v248
	v_fmac_f32_e32 v84, v246, v248
	v_fmac_f32_e32 v85, v247, v248
	s_branch .Lrf_join
.Lrf_t6_7:
	v_fmac_f32_e32 v78, v240, v248
	v_fmac_f32_e32 v79, v241, v248
	v_fmac_f32_e32 v80, v242, v248
	v_fmac_f32_e32 v81, v243, v248
	v_fmac_f32_e32 v74, v244, v248
	v_fmac_f32_e32 v75, v245, v248
	v_fmac_f32_e32 v76, v246, v248
	v_fmac_f32_e32 v77, v247, v248
	s_branch .Lrf_join
.Lrf_t7_15:
	s_cmp_ge_u32 s74, 22
	s_cbranch_scc1 .Lrf_t11_15
	s_cmp_ge_u32 s74, 18
	s_cbranch_scc1 .Lrf_t9_11
	s_cmp_ge_u32 s74, 16
	s_cbranch_scc1 .Lrf_t8_9
	v_fmac_f32_e32 v70, v240, v248
	v_fmac_f32_e32 v71, v241, v248
	v_fmac_f32_e32 v72, v242, v248
	v_fmac_f32_e32 v73, v243, v248
	v_fmac_f32_e32 v66, v244, v248
	v_fmac_f32_e32 v67, v245, v248
	v_fmac_f32_e32 v68, v246, v248
	v_fmac_f32_e32 v69, v247, v248
	s_branch .Lrf_join
.Lrf_t8_9:
	v_fmac_f32_e32 v62, v240, v248
	v_fmac_f32_e32 v63, v241, v248
	v_fmac_f32_e32 v64, v242, v248
	v_fmac_f32_e32 v65, v243, v248
	v_fmac_f32_e32 v58, v244, v248
	v_fmac_f32_e32 v59, v245, v248
	v_fmac_f32_e32 v60, v246, v248
	v_fmac_f32_e32 v61, v247, v248
	s_branch .Lrf_join
.Lrf_t9_11:
	s_cmp_ge_u32 s74, 20
	s_cbranch_scc1 .Lrf_t10_11
	v_fmac_f32_e32 v54, v240, v248
	v_fmac_f32_e32 v55, v241, v248
	v_fmac_f32_e32 v56, v242, v248
	v_fmac_f32_e32 v57, v243, v248
	v_fmac_f32_e32 v50, v244, v248
	v_fmac_f32_e32 v51, v245, v248
	v_fmac_f32_e32 v52, v246, v248
	v_fmac_f32_e32 v53, v247, v248
	s_branch .Lrf_join
.Lrf_t10_11:
	v_fmac_f32_e32 v46, v240, v248
	v_fmac_f32_e32 v47, v241, v248
	v_fmac_f32_e32 v48, v242, v248
	v_fmac_f32_e32 v49, v243, v248
	v_fmac_f32_e32 v42, v244, v248
	v_fmac_f32_e32 v43, v245, v248
	v_fmac_f32_e32 v44, v246, v248
	v_fmac_f32_e32 v45, v247, v248
	s_branch .Lrf_join
.Lrf_t11_15:
	s_cmp_ge_u32 s74, 26
	s_cbranch_scc1 .Lrf_t13_15
	s_cmp_ge_u32 s74, 24
	s_cbranch_scc1 .Lrf_t12_13
	v_fmac_f32_e32 v38, v240, v248
	v_fmac_f32_e32 v39, v241, v248
	v_fmac_f32_e32 v40, v242, v248
	v_fmac_f32_e32 v41, v243, v248
	v_fmac_f32_e32 v34, v244, v248
	v_fmac_f32_e32 v35, v245, v248
	v_fmac_f32_e32 v36, v246, v248
	v_fmac_f32_e32 v37, v247, v248
	s_branch .Lrf_join
.Lrf_t12_13:
	v_fmac_f32_e32 v30, v240, v248
	v_fmac_f32_e32 v31, v241, v248
	v_fmac_f32_e32 v32, v242, v248
	v_fmac_f32_e32 v33, v243, v248
	v_fmac_f32_e32 v26, v244, v248
	v_fmac_f32_e32 v27, v245, v248
	v_fmac_f32_e32 v28, v246, v248
	v_fmac_f32_e32 v29, v247, v248
	s_branch .Lrf_join
.Lrf_t13_15:
	s_cmp_ge_u32 s74, 28
	s_cbranch_scc1 .Lrf_t14_15
	v_fmac_f32_e32 v22, v240, v248
	v_fmac_f32_e32 v23, v241, v248
	v_fmac_f32_e32 v24, v242, v248
	v_fmac_f32_e32 v25, v243, v248
	v_fmac_f32_e32 v18, v244, v248
	v_fmac_f32_e32 v19, v245, v248
	v_fmac_f32_e32 v20, v246, v248
	v_fmac_f32_e32 v21, v247, v248
	s_branch .Lrf_join
.Lrf_t14_15:
	v_fmac_f32_e32 v14, v240, v248
	v_fmac_f32_e32 v15, v241, v248
	v_fmac_f32_e32 v16, v242, v248
	v_fmac_f32_e32 v17, v243, v248
	v_fmac_f32_e32 v10, v244, v248
	v_fmac_f32_e32 v11, v245, v248
	v_fmac_f32_e32 v12, v246, v248
	v_fmac_f32_e32 v13, v247, v248
	s_branch .Lrf_join
.Lrf_join:
	s_waitcnt vmcnt(8)
	s_waitcnt lgkmcnt(0)
	s_barrier
	s_setprio 1
	s_waitcnt lgkmcnt(0)
	v_mfma_f32_16x16x32_bf16 v[62:65], v[130:133], v[188:191], v[62:65]
	v_mfma_f32_16x16x32_bf16 v[58:61], v[158:161], v[188:191], v[58:61]
	v_mfma_f32_16x16x32_bf16 v[46:49], v[130:133], v[196:199], v[46:49]
	v_mfma_f32_16x16x32_bf16 v[42:45], v[158:161], v[196:199], v[42:45]
	v_mfma_f32_16x16x32_bf16 v[30:33], v[130:133], v[204:207], v[30:33]
	v_mfma_f32_16x16x32_bf16 v[26:29], v[158:161], v[204:207], v[26:29]
	v_mfma_f32_16x16x32_bf16 v[14:17], v[130:133], v[212:215], v[14:17]
	v_mfma_f32_16x16x32_bf16 v[10:13], v[158:161], v[212:215], v[10:13]
	v_mfma_f32_16x16x32_bf16 v[62:65], v[134:137], v[192:195], v[62:65]
	v_mfma_f32_16x16x32_bf16 v[58:61], v[162:165], v[192:195], v[58:61]
	v_mfma_f32_16x16x32_bf16 v[46:49], v[134:137], v[200:203], v[46:49]
	v_mfma_f32_16x16x32_bf16 v[42:45], v[162:165], v[200:203], v[42:45]
	v_mfma_f32_16x16x32_bf16 v[30:33], v[134:137], v[208:211], v[30:33]
	v_mfma_f32_16x16x32_bf16 v[26:29], v[162:165], v[208:211], v[26:29]
	v_mfma_f32_16x16x32_bf16 v[14:17], v[134:137], v[216:219], v[14:17]
	v_mfma_f32_16x16x32_bf16 v[10:13], v[162:165], v[216:219], v[10:13]
	s_setprio 0
	s_setprio 1
	v_mfma_f32_16x16x32_bf16 v[54:57], v[166:169], v[188:191], v[54:57]
	v_mfma_f32_16x16x32_bf16 v[50:53], v[180:183], v[188:191], v[50:53]
	v_mfma_f32_16x16x32_bf16 v[38:41], v[166:169], v[196:199], v[38:41]
	v_mfma_f32_16x16x32_bf16 v[34:37], v[180:183], v[196:199], v[34:37]
	v_mfma_f32_16x16x32_bf16 v[22:25], v[166:169], v[204:207], v[22:25]
	v_mfma_f32_16x16x32_bf16 v[18:21], v[180:183], v[204:207], v[18:21]
	v_mfma_f32_16x16x32_bf16 v[6:9], v[166:169], v[212:215], v[6:9]
	v_mfma_f32_16x16x32_bf16 v[2:5], v[180:183], v[212:215], v[2:5]
	v_mfma_f32_16x16x32_bf16 v[54:57], v[176:179], v[192:195], v[54:57]
	v_mfma_f32_16x16x32_bf16 v[50:53], v[184:187], v[192:195], v[50:53]
	v_mfma_f32_16x16x32_bf16 v[38:41], v[176:179], v[200:203], v[38:41]
	v_mfma_f32_16x16x32_bf16 v[34:37], v[184:187], v[200:203], v[34:37]
	v_mfma_f32_16x16x32_bf16 v[22:25], v[176:179], v[208:211], v[22:25]
	v_mfma_f32_16x16x32_bf16 v[18:21], v[184:187], v[208:211], v[18:21]
	v_mfma_f32_16x16x32_bf16 v[6:9], v[176:179], v[216:219], v[6:9]
	v_mfma_f32_16x16x32_bf16 v[2:5], v[184:187], v[216:219], v[2:5]
	s_setprio 0
	s_barrier
	s_add_i32 s77, s74, 2
	s_lshr_b32 s32, s77, 4
	s_lshl_b32 s32, s32, 20
	s_bfe_u32 s100, s77, 0x20002
	s_lshl_b32 s100, s100, 17
	s_or_b32 s32, s32, s100
	s_and_b32 s100, s77, 2
	s_lshl_b32 s100, s100, 8
	s_or_b32 s32, s32, s100
	s_and_b32 s100, s92, 1
	s_lshr_b32 s32, s32, s100
	s_add_u32 s100, s94, s32
	s_addc_u32 s101, s95, 0
	s_cmp_eq_u32 s92, 0
	s_cbranch_scc0 .Lrf_ld_m1
	global_load_dwordx4 v[240:243], v250, s[100:101]
	global_load_dwordx4 v[244:247], v250, s[100:101] offset:16
	s_branch .Lrf_ld_done
; #define PG8_STAGE(bufoff, gbase, voff) do { _Pragma("unroll") for (int _i = 0; _i < 2; ++_i) \
;         __builtin_amdgcn_global_load_lds((const unsigned*)((const char*)(gbase) + (voff)[_i]), (PG8_LAS unsigned*)(lds + (bufoff) + ldsw + _i * 8192), 16, 0, 0); } while (0)
; #define PG8_LDA(dst, b, h) do { _Pragma("unroll") for (int m = 0; m < 4; ++m) _Pragma("unroll") for (int k = 0; k < 2; ++k) dst[m][k] = *(const PG8_LAS bf16x8*)(lds + PG8_SA(b, h) + aoff + m * 2048 + k * 1024); } while (0)
; #define PG8_LDB(dst, b, h) do { _Pragma("unroll") for (int n = 0; n < 2; ++n) _Pragma("unroll") for (int k = 0; k < 2; ++k) dst[n][k] = *(const PG8_LAS bf16x8*)(lds + PG8_SB(b, h) + boff + n * 2048 + k * 1024); } while (0)
; #define PG8_MMA(ai, bj, At, Bt) do { __builtin_amdgcn_s_setprio(1); _Pragma("unroll") for (int m = 0; m < 4; ++m) _Pragma("unroll") for (int n = 0; n < 2; ++n) _Pragma("unroll") for (int k = 0; k < 2; ++k) \
;         acc[ai][bj][m][n] = __builtin_amdgcn_mfma_f32_16x16x32_bf16(Bt[n][k], At[m][k], acc[ai][bj][m][n], 0, 0, 0); __builtin_amdgcn_s_setprio(0); } while (0)
; #define PG8_WAIT_V(n) asm volatile("s_waitcnt vmcnt(" #n ")" ::: "memory")
; #define PG8_WAIT_L(n) asm volatile("s_waitcnt lgkmcnt(" #n ")" ::: "memory")
; #define PG8_BAR __builtin_amdgcn_s_barrier()
; #define PG8_SCHED __builtin_amdgcn_sched_barrier(0)
;     __device__ __forceinline__ void operator()(const f32x4 (&acc)[2][2][4][2], const Unit& u, int wr, int wc, int fr, int fq, const PG8_LAS float* tab) const {
;     ...
;                 const float ra = tab[ai * HALF + wr * 64 + m * 16 + fr];
; template <class Epi, class Sched, bool ALIGN_EPI = false, bool SP2 = true>
; __device__ __forceinline__ void gemm_phase(PG8_LAS unsigned char* lds, const Gemm g, const Sched& S, const Epi& E, int wave_s) {
;     ...
;             PG8_LDB(B0, 1, 0); PG8_LDB(B1, 1, 1); PG8_SCHED; PG8_LDA(At, 1, 0); PG8_STAGE(PG8_SA(0, 1), a2 + hstepA, voffA);
;             PG8_WAIT_V(8); PG8_WAIT_L(0); PG8_BAR; PG8_MMA(0, 0, At, B0); PG8_MMA(0, 1, At, B1); PG8_BAR; PG8_SCHED;
;             PG8_LDA(At, 1, 1); PG8_STAGE(PG8_SB(1, 0), b3, voffB); PG8_STAGE(PG8_SB(1, 1), b3 + hstepB, voffB); PG8_STAGE(PG8_SA(1, 0), a3, voffA);
;             PG8_WAIT_V(8); PG8_WAIT_L(0); PG8_BAR; PG8_MMA(1, 0, At, B0); PG8_MMA(1, 1, At, B1); PG8_BAR; PG8_SCHED;
.Lrf_ld_m1:
	global_load_dwordx4 v[228:231], v250, s[100:101]
	global_load_dword v232, v250, s[100:101]
.Lrf_ld_done:
	s_add_i32 s75, 0, 0x18000
	s_add_i32 s76, 0, 0x1c000
	v_add_u32_e32 v162, s75, v170
	v_add_u32_e32 v175, s76, v170
	ds_read_b128 v[130:133], v162
	ds_read_b128 v[134:137], v162 offset:1024
	ds_read_b128 v[158:161], v162 offset:2048
	ds_read_b128 v[162:165], v162 offset:3072
	ds_read_b128 v[166:169], v175
	ds_read_b128 v[176:179], v175 offset:1024
	ds_read_b128 v[180:183], v175 offset:2048
	ds_read_b128 v[184:187], v175 offset:3072
	s_add_u32 s24, s28, 0x140000
	s_addc_u32 s25, s29, 0
	s_mov_b32 m0, s42
	v_lshl_add_u64 v[226:227], s[24:25], 0, v[144:145]
	ds_read_b128 v[188:191], v174 offset:32768
	ds_read_b128 v[192:195], v174 offset:33792
	ds_read_b128 v[196:199], v174 offset:34816
	ds_read_b128 v[200:203], v174 offset:35840
	ds_read_b128 v[204:207], v174 offset:36864
	ds_read_b128 v[208:211], v174 offset:37888
	ds_read_b128 v[212:215], v174 offset:38912
	ds_read_b128 v[216:219], v174 offset:39936
	global_load_lds_dwordx4 v[226:227], off
	v_lshl_add_u64 v[226:227], s[24:25], 0, v[140:141]
	s_mov_b32 m0, s43
	s_nop 0
	global_load_lds_dwordx4 v[226:227], off
	s_waitcnt vmcnt(10)
	s_waitcnt lgkmcnt(0)
	s_barrier
	s_setprio 1
	s_waitcnt lgkmcnt(0)
	v_mfma_f32_16x16x32_bf16 v[126:129], v[130:133], v[188:191], v[126:129]
	v_mfma_f32_16x16x32_bf16 v[122:125], v[158:161], v[188:191], v[122:125]
	v_mfma_f32_16x16x32_bf16 v[110:113], v[130:133], v[196:199], v[110:113]
	v_mfma_f32_16x16x32_bf16 v[106:109], v[158:161], v[196:199], v[106:109]
	v_mfma_f32_16x16x32_bf16 v[94:97], v[130:133], v[204:207], v[94:97]
	v_mfma_f32_16x16x32_bf16 v[90:93], v[158:161], v[204:207], v[90:93]
	v_mfma_f32_16x16x32_bf16 v[78:81], v[130:133], v[212:215], v[78:81]
	v_mfma_f32_16x16x32_bf16 v[74:77], v[158:161], v[212:215], v[74:77]
	v_mfma_f32_16x16x32_bf16 v[126:129], v[134:137], v[192:195], v[126:129]
	v_mfma_f32_16x16x32_bf16 v[122:125], v[162:165], v[192:195], v[122:125]
	v_mfma_f32_16x16x32_bf16 v[110:113], v[134:137], v[200:203], v[110:113]
	v_mfma_f32_16x16x32_bf16 v[106:109], v[162:165], v[200:203], v[106:109]
	v_mfma_f32_16x16x32_bf16 v[94:97], v[134:137], v[208:211], v[94:97]
	v_mfma_f32_16x16x32_bf16 v[90:93], v[162:165], v[208:211], v[90:93]
	v_mfma_f32_16x16x32_bf16 v[78:81], v[134:137], v[216:219], v[78:81]
	v_mfma_f32_16x16x32_bf16 v[74:77], v[162:165], v[216:219], v[74:77]
	s_setprio 0
	s_setprio 1
	v_mfma_f32_16x16x32_bf16 v[118:121], v[166:169], v[188:191], v[118:121]
	v_mfma_f32_16x16x32_bf16 v[114:117], v[180:183], v[188:191], v[114:117]
	v_mfma_f32_16x16x32_bf16 v[102:105], v[166:169], v[196:199], v[102:105]
	v_mfma_f32_16x16x32_bf16 v[98:101], v[180:183], v[196:199], v[98:101]
	v_mfma_f32_16x16x32_bf16 v[86:89], v[166:169], v[204:207], v[86:89]
	v_mfma_f32_16x16x32_bf16 v[82:85], v[180:183], v[204:207], v[82:85]
	v_mfma_f32_16x16x32_bf16 v[70:73], v[166:169], v[212:215], v[70:73]
	v_mfma_f32_16x16x32_bf16 v[66:69], v[180:183], v[212:215], v[66:69]
	v_mfma_f32_16x16x32_bf16 v[118:121], v[176:179], v[192:195], v[118:121]
	v_mfma_f32_16x16x32_bf16 v[114:117], v[184:187], v[192:195], v[114:117]
	v_mfma_f32_16x16x32_bf16 v[102:105], v[176:179], v[200:203], v[102:105]
	v_mfma_f32_16x16x32_bf16 v[98:101], v[184:187], v[200:203], v[98:101]
	v_mfma_f32_16x16x32_bf16 v[86:89], v[176:179], v[208:211], v[86:89]
	v_mfma_f32_16x16x32_bf16 v[82:85], v[184:187], v[208:211], v[82:85]
	v_mfma_f32_16x16x32_bf16 v[70:73], v[176:179], v[216:219], v[70:73]
	v_mfma_f32_16x16x32_bf16 v[66:69], v[184:187], v[216:219], v[66:69]
	s_setprio 0
	s_barrier
	s_add_i32 s77, s74, 2
	s_lshr_b32 s77, s77, 2
	s_and_b32 s32, s77, 3
	s_lshl_b32 s32, s32, 6
	s_lshr_b32 s77, s77, 2
	s_lshl_b32 s77, s77, 9
	s_or_b32 s77, s77, s32
	v_add_u32_e32 v253, s77, v252
	ds_read_b32 v251, v253
	s_add_i32 s24, s75, s34
	v_lshl_add_u64 v[146:147], v[146:147], 0, s[78:79]
	s_mov_b32 m0, s24
	ds_read_b128 v[188:191], v174 offset:49152
	ds_read_b128 v[192:195], v174 offset:50176
	ds_read_b128 v[196:199], v174 offset:51200
	ds_read_b128 v[200:203], v174 offset:52224
	ds_read_b128 v[204:207], v174 offset:53248
	ds_read_b128 v[208:211], v174 offset:54272
	ds_read_b128 v[212:215], v174 offset:55296
	ds_read_b128 v[216:219], v174 offset:56320
	global_load_lds_dwordx4 v[146:147], off
	s_add_i32 m0, s24, 0x2000
	s_add_u32 s24, s26, 0x80080
	v_lshl_add_u64 v[146:147], v[220:221], 0, s[78:79]
	s_addc_u32 s25, s27, 0
	s_add_i32 s26, s76, s34
	global_load_lds_dwordx4 v[146:147], off
	v_lshl_add_u64 v[146:147], s[24:25], 0, v[142:143]
	s_mov_b32 m0, s26
	s_nop 0
	global_load_lds_dwordx4 v[146:147], off
	v_lshl_add_u64 v[146:147], s[24:25], 0, v[138:139]
	s_add_i32 m0, s26, 0x2000
	s_nop 0
	global_load_lds_dwordx4 v[146:147], off
	v_lshl_add_u64 v[146:147], v[222:223], 0, s[78:79]
	s_mov_b32 m0, s40
	s_nop 0
	global_load_lds_dwordx4 v[146:147], off
	v_lshl_add_u64 v[146:147], v[224:225], 0, s[78:79]
	s_mov_b32 m0, s41
	s_nop 0
	global_load_lds_dwordx4 v[146:147], off
	s_waitcnt vmcnt(10)
	s_waitcnt lgkmcnt(0)
	v_rcp_f32_e32 v248, v251
	s_barrier
; #define GAS __attribute__((address_space(1)))
; __device__ __forceinline__ unsigned cvt_pk_bf16(float lo, float hi) { unsigned r; asm volatile("v_cvt_pk_bf16_f32 %0, %1, %2" : "=v"(r) : "v"(lo), "v"(hi)); return r; }
; __device__ __forceinline__ float bf_lo(unsigned w) { return __uint_as_float(w << 16); }
; #define PG8_BAR __builtin_amdgcn_s_barrier()
;     __device__ __forceinline__ void operator()(const f32x4 (&acc)[2][2][4][2], const Unit& u, int wr, int wc, int fr, int fq, const PG8_LAS float* tab) const {
; #pragma unroll
;         for (int ai = 0; ai < 2; ++ai)
; #pragma unroll
;             for (int m = 0; m < 4; ++m) {
;                 const int row = u.pm * BM + ai * HALF + wr * 64 + m * 16 + fr;
;                 const float ra = tab[ai * HALF + wr * 64 + m * 16 + fr];
;                 const GAS float* xo = (const GAS float*)(row < 16384 ? x0a + (size_t)row * 2048 : x0b + (size_t)(row - 16384) * 2048);
;                 GAS bf16_t* xr = (GAS bf16_t*)XN + (size_t)row * 2048;
;                 float ssq = 0.f;
; #pragma unroll
;                 for (int bj = 0; bj < 2; ++bj) {
;                     const int col0 = u.pn * BM + bj * HALF + wc * 32 + 8 * fq;
;                     f32x4 a0, a1;
;                     if (mode == 0) { a0 = *(const GAS f32x4*)(xo + col0); a1 = *(const GAS f32x4*)(xo + col0 + 4); }
;                     else { const u32x4 w = *(const GAS u32x4*)(xr + col0);
;                         a0 = (f32x4){bf_lo(w.x), bf_hi(w.x), bf_lo(w.y), bf_hi(w.y)}; a1 = (f32x4){bf_lo(w.z), bf_hi(w.z), bf_lo(w.w), bf_hi(w.w)}; }
;                     const f32x4 v0 = a0 + acc[ai][bj][m][0] * ra, v1 = a1 + acc[ai][bj][m][1] * ra;
;                     ssq += (v0[0] * v0[0] + v0[1] * v0[1]) + (v0[2] * v0[2] + v0[3] * v0[3]) + (v1[0] * v1[0] + v1[1] * v1[1]) + (v1[2] * v1[2] + v1[3] * v1[3]);
;                     u32x4 w; w.x = cvt_pk_bf16(v0[0], v0[1]); w.y = cvt_pk_bf16(v0[2], v0[3]); w.z = cvt_pk_bf16(v1[0], v1[1]); w.w = cvt_pk_bf16(v1[2], v1[3]);
;                     *(GAS u32x4*)(xr + col0) = w;
; template <class Epi, class Sched, bool ALIGN_EPI = false, bool SP2 = true>
; __device__ __forceinline__ void gemm_phase(PG8_LAS unsigned char* lds, const Gemm g, const Sched& S, const Epi& E, int wave_s) {
;     ...
;             PG8_WAIT_V(8); PG8_WAIT_L(0); PG8_BAR; PG8_MMA(1, 0, At, B0); PG8_MMA(1, 1, At, B1); PG8_BAR; PG8_SCHED;
	s_setprio 1
	s_waitcnt lgkmcnt(0)
	v_mfma_f32_16x16x32_bf16 v[62:65], v[130:133], v[188:191], v[62:65]
	v_mfma_f32_16x16x32_bf16 v[58:61], v[158:161], v[188:191], v[58:61]
	v_mfma_f32_16x16x32_bf16 v[46:49], v[130:133], v[196:199], v[46:49]
	v_mfma_f32_16x16x32_bf16 v[42:45], v[158:161], v[196:199], v[42:45]
	v_mfma_f32_16x16x32_bf16 v[30:33], v[130:133], v[204:207], v[30:33]
	v_mfma_f32_16x16x32_bf16 v[26:29], v[158:161], v[204:207], v[26:29]
	v_mfma_f32_16x16x32_bf16 v[14:17], v[130:133], v[212:215], v[14:17]
	v_mfma_f32_16x16x32_bf16 v[10:13], v[158:161], v[212:215], v[10:13]
	v_mfma_f32_16x16x32_bf16 v[62:65], v[134:137], v[192:195], v[62:65]
	v_mfma_f32_16x16x32_bf16 v[58:61], v[162:165], v[192:195], v[58:61]
	v_mfma_f32_16x16x32_bf16 v[46:49], v[134:137], v[200:203], v[46:49]
	v_mfma_f32_16x16x32_bf16 v[42:45], v[162:165], v[200:203], v[42:45]
	v_mfma_f32_16x16x32_bf16 v[30:33], v[134:137], v[208:211], v[30:33]
	v_mfma_f32_16x16x32_bf16 v[26:29], v[162:165], v[208:211], v[26:29]
	v_mfma_f32_16x16x32_bf16 v[14:17], v[134:137], v[216:219], v[14:17]
	v_mfma_f32_16x16x32_bf16 v[10:13], v[162:165], v[216:219], v[10:13]
	s_setprio 0
	s_setprio 1
	v_mfma_f32_16x16x32_bf16 v[54:57], v[166:169], v[188:191], v[54:57]
	v_mfma_f32_16x16x32_bf16 v[50:53], v[180:183], v[188:191], v[50:53]
	v_mfma_f32_16x16x32_bf16 v[38:41], v[166:169], v[196:199], v[38:41]
	v_mfma_f32_16x16x32_bf16 v[34:37], v[180:183], v[196:199], v[34:37]
	v_mfma_f32_16x16x32_bf16 v[22:25], v[166:169], v[204:207], v[22:25]
	v_mfma_f32_16x16x32_bf16 v[18:21], v[180:183], v[204:207], v[18:21]
	v_mfma_f32_16x16x32_bf16 v[6:9], v[166:169], v[212:215], v[6:9]
	v_mfma_f32_16x16x32_bf16 v[2:5], v[180:183], v[212:215], v[2:5]
	v_mfma_f32_16x16x32_bf16 v[54:57], v[176:179], v[192:195], v[54:57]
	v_mfma_f32_16x16x32_bf16 v[50:53], v[184:187], v[192:195], v[50:53]
	v_mfma_f32_16x16x32_bf16 v[38:41], v[176:179], v[200:203], v[38:41]
	v_mfma_f32_16x16x32_bf16 v[34:37], v[184:187], v[200:203], v[34:37]
	v_mfma_f32_16x16x32_bf16 v[22:25], v[176:179], v[208:211], v[22:25]
	v_mfma_f32_16x16x32_bf16 v[18:21], v[184:187], v[208:211], v[18:21]
	v_mfma_f32_16x16x32_bf16 v[6:9], v[176:179], v[216:219], v[6:9]
	v_mfma_f32_16x16x32_bf16 v[2:5], v[184:187], v[216:219], v[2:5]
	s_setprio 0
	s_barrier
	s_add_i32 s74, s74, 2
	s_add_u32 s72, s72, 0x100
	s_addc_u32 s73, s73, 0
	s_cmp_gt_u32 s74, 29
	s_mov_b64 s[24:25], s[6:7]
	s_cbranch_scc0 .LBB0_608
	s_and_b64 vcc, exec, s[16:17]
	s_cbranch_vccz .LBB0_611
	s_barrier
.LBB0_611:
	s_lshl_b32 s6, s3, 20
	s_lshl_b32 s7, s0, 9
	s_add_u32 s6, s6, s7
	s_add_u32 s24, s58, s6
	s_addc_u32 s25, s59, 0
	v_lshlrev_b32_e32 v146, 12, v1
	v_lshl_add_u32 v146, v173, 1, v146
	s_lshl_b32 s6, s3, 10
	s_add_u32 s26, s12, s6
	s_addc_u32 s27, s13, 0
	ds_read_b32 v130, v252 offset:0
	ds_read_b32 v132, v252 offset:64
	ds_read_b32 v134, v252 offset:128
	ds_read_b32 v136, v252 offset:192
	ds_read_b32 v131, v252 offset:512
	ds_read_b32 v133, v252 offset:576
	ds_read_b32 v135, v252 offset:640
	ds_read_b32 v137, v252 offset:704
	s_waitcnt vmcnt(8)
	s_cmp_eq_u32 s92, 0
	s_cbranch_scc1 .Lrf_epi_f32
	v_lshlrev_b32_e32 v240, 16, v228
	v_and_b32_e32 v241, 0xffff0000, v228
	v_lshlrev_b32_e32 v242, 16, v229
	v_and_b32_e32 v243, 0xffff0000, v229
	v_lshlrev_b32_e32 v244, 16, v230
	v_and_b32_e32 v245, 0xffff0000, v230
	v_lshlrev_b32_e32 v246, 16, v231
	v_and_b32_e32 v247, 0xffff0000, v231
.Lrf_epi_f32:
	v_fmac_f32_e32 v6, v240, v248
	v_fmac_f32_e32 v7, v241, v248
	v_fmac_f32_e32 v8, v242, v248
	v_fmac_f32_e32 v9, v243, v248
	v_fmac_f32_e32 v2, v244, v248
	v_fmac_f32_e32 v3, v245, v248
	v_fmac_f32_e32 v4, v246, v248
	v_fmac_f32_e32 v5, v247, v248
	s_waitcnt lgkmcnt(0)
	v_pk_mul_f32 v[126:127], v[126:127], v[130:131] op_sel_hi:[1,0]
	v_pk_mul_f32 v[128:129], v[128:129], v[130:131] op_sel_hi:[1,0]
	v_pk_mul_f32 v[122:123], v[122:123], v[130:131] op_sel_hi:[1,0]
	v_pk_mul_f32 v[124:125], v[124:125], v[130:131] op_sel_hi:[1,0]
	v_cvt_pk_bf16_f32 v158, v126, v127
	v_cvt_pk_bf16_f32 v159, v128, v129
	v_cvt_pk_bf16_f32 v160, v122, v123
	v_cvt_pk_bf16_f32 v161, v124, v125
	s_mov_b64 s[72:73], s[24:25]
	global_store_dwordx4 v146, v[158:161], s[72:73] offset:0
	v_mul_f32_e32 v175, v127, v127
	v_mul_f32_e32 v253, v129, v129
	v_fmac_f32_e32 v175, v126, v126
	v_fmac_f32_e32 v253, v128, v128
	v_add_f32_e32 v147, v175, v253
	v_mul_f32_e32 v253, v123, v123
	v_fmac_f32_e32 v253, v122, v122
	v_mul_f32_e32 v175, v125, v125
	v_add_f32_e32 v147, v253, v147
	v_fmac_f32_e32 v175, v124, v124
	v_add_f32_e32 v147, v175, v147
	v_pk_mul_f32 v[118:119], v[118:119], v[130:131] op_sel_hi:[1,0]
	v_pk_mul_f32 v[120:121], v[120:121], v[130:131] op_sel_hi:[1,0]
	v_pk_mul_f32 v[114:115], v[114:115], v[130:131] op_sel_hi:[1,0]
	v_pk_mul_f32 v[116:117], v[116:117], v[130:131] op_sel_hi:[1,0]
	v_cvt_pk_bf16_f32 v162, v118, v119
	v_cvt_pk_bf16_f32 v163, v120, v121
	v_cvt_pk_bf16_f32 v164, v114, v115
	v_cvt_pk_bf16_f32 v165, v116, v117
	global_store_dwordx4 v146, v[162:165], s[72:73] offset:256
	v_mul_f32_e32 v175, v119, v119
	v_mul_f32_e32 v253, v121, v121
	v_fmac_f32_e32 v175, v118, v118
	v_fmac_f32_e32 v253, v120, v120
	v_add_f32_e32 v166, v175, v253
	v_mul_f32_e32 v253, v115, v115
	v_fmac_f32_e32 v253, v114, v114
	v_mul_f32_e32 v175, v117, v117
	v_add_f32_e32 v166, v253, v166
	v_fmac_f32_e32 v175, v116, v116
	v_add_f32_e32 v166, v175, v166
	v_add_f32_e32 v166, v147, v166
	ds_bpermute_b32 v167, v172, v166
	v_pk_mul_f32 v[110:111], v[110:111], v[132:133] op_sel_hi:[1,0]
	v_pk_mul_f32 v[112:113], v[112:113], v[132:133] op_sel_hi:[1,0]
	v_pk_mul_f32 v[106:107], v[106:107], v[132:133] op_sel_hi:[1,0]
; #define GAS __attribute__((address_space(1)))
; __device__ __forceinline__ unsigned cvt_pk_bf16(float lo, float hi) { unsigned r; asm volatile("v_cvt_pk_bf16_f32 %0, %1, %2" : "=v"(r) : "v"(lo), "v"(hi)); return r; }
; __device__ __forceinline__ float bf_lo(unsigned w) { return __uint_as_float(w << 16); }
; __device__ __forceinline__ float bf_hi(unsigned w) { return __uint_as_float(w & 0xffff0000u); }
; __device__ __forceinline__ float shx(float v, int lane, int mask) { return __int_as_float(__builtin_amdgcn_ds_bpermute((lane ^ mask) << 2, __float_as_int(v))); }
; __device__ __forceinline__ float x32_sum(float v) { auto rr = __builtin_amdgcn_permlane32_swap(__float_as_uint(v), __float_as_uint(v), false, false); return __uint_as_float(rr[0]) + __uint_as_float(rr[1]); }
;     __device__ __forceinline__ void operator()(const f32x4 (&acc)[2][2][4][2], const Unit& u, int wr, int wc, int fr, int fq, const PG8_LAS float* tab) const {
;     ...
;                 for (int bj = 0; bj < 2; ++bj) {
;                     const int col0 = u.pn * BM + bj * HALF + wc * 32 + 8 * fq;
;                     f32x4 a0, a1;
;                     if (mode == 0) { a0 = *(const GAS f32x4*)(xo + col0); a1 = *(const GAS f32x4*)(xo + col0 + 4); }
;                     else { const u32x4 w = *(const GAS u32x4*)(xr + col0);
;                         a0 = (f32x4){bf_lo(w.x), bf_hi(w.x), bf_lo(w.y), bf_hi(w.y)}; a1 = (f32x4){bf_lo(w.z), bf_hi(w.z), bf_lo(w.w), bf_hi(w.w)}; }
;                     const f32x4 v0 = a0 + acc[ai][bj][m][0] * ra, v1 = a1 + acc[ai][bj][m][1] * ra;
;                     ssq += (v0[0] * v0[0] + v0[1] * v0[1]) + (v0[2] * v0[2] + v0[3] * v0[3]) + (v1[0] * v1[0] + v1[1] * v1[1]) + (v1[2] * v1[2] + v1[3] * v1[3]);
;                     u32x4 w; w.x = cvt_pk_bf16(v0[0], v0[1]); w.y = cvt_pk_bf16(v0[2], v0[3]); w.z = cvt_pk_bf16(v1[0], v1[1]); w.w = cvt_pk_bf16(v1[2], v1[3]);
;                     *(GAS u32x4*)(xr + col0) = w;
;                 }
;                 { const int ln = fr + 16 * fq; ssq += shx(ssq, ln, 16); ssq = x32_sum(ssq); }
;                 if (fq == 0) unsafeAtomicAdd(SSn + row, ssq);
	v_pk_mul_f32 v[108:109], v[108:109], v[132:133] op_sel_hi:[1,0]
	v_cvt_pk_bf16_f32 v158, v110, v111
	v_cvt_pk_bf16_f32 v159, v112, v113
	v_cvt_pk_bf16_f32 v160, v106, v107
	v_cvt_pk_bf16_f32 v161, v108, v109
	s_add_u32 s72, s24, 0x10000
	s_addc_u32 s73, s25, 0
	global_store_dwordx4 v146, v[158:161], s[72:73] offset:0
	v_mul_f32_e32 v175, v111, v111
	v_mul_f32_e32 v253, v113, v113
	v_fmac_f32_e32 v175, v110, v110
	v_fmac_f32_e32 v253, v112, v112
	v_add_f32_e32 v147, v175, v253
	v_mul_f32_e32 v253, v107, v107
	v_fmac_f32_e32 v253, v106, v106
	v_mul_f32_e32 v175, v109, v109
	v_add_f32_e32 v147, v253, v147
	v_fmac_f32_e32 v175, v108, v108
	v_add_f32_e32 v147, v175, v147
	v_pk_mul_f32 v[102:103], v[102:103], v[132:133] op_sel_hi:[1,0]
	v_pk_mul_f32 v[104:105], v[104:105], v[132:133] op_sel_hi:[1,0]
	v_pk_mul_f32 v[98:99], v[98:99], v[132:133] op_sel_hi:[1,0]
	v_pk_mul_f32 v[100:101], v[100:101], v[132:133] op_sel_hi:[1,0]
	v_cvt_pk_bf16_f32 v162, v102, v103
	v_cvt_pk_bf16_f32 v163, v104, v105
	v_cvt_pk_bf16_f32 v164, v98, v99
	v_cvt_pk_bf16_f32 v165, v100, v101
	global_store_dwordx4 v146, v[162:165], s[72:73] offset:256
	v_mul_f32_e32 v175, v103, v103
	v_mul_f32_e32 v253, v105, v105
	v_fmac_f32_e32 v175, v102, v102
	v_fmac_f32_e32 v253, v104, v104
	v_add_f32_e32 v168, v175, v253
	v_mul_f32_e32 v253, v99, v99
	v_fmac_f32_e32 v253, v98, v98
	v_mul_f32_e32 v175, v101, v101
	v_add_f32_e32 v168, v253, v168
	v_fmac_f32_e32 v175, v100, v100
	v_add_f32_e32 v168, v175, v168
	v_add_f32_e32 v168, v147, v168
	s_waitcnt lgkmcnt(0)
	v_add_f32_e32 v166, v166, v167
	v_mov_b32_e32 v167, v166
	s_nop 1
	v_permlane32_swap_b32_e32 v166, v167
	s_and_saveexec_b64 s[6:7], s[8:9]
	v_add_f32_e32 v166, v166, v167
	v_lshlrev_b32_e32 v167, 2, v1
	global_atomic_add_f32 v167, v166, s[26:27] offset:0
	s_mov_b64 exec, s[6:7]
	ds_bpermute_b32 v169, v172, v168
	v_pk_mul_f32 v[94:95], v[94:95], v[134:135] op_sel_hi:[1,0]
	v_pk_mul_f32 v[96:97], v[96:97], v[134:135] op_sel_hi:[1,0]
	v_pk_mul_f32 v[90:91], v[90:91], v[134:135] op_sel_hi:[1,0]
	v_pk_mul_f32 v[92:93], v[92:93], v[134:135] op_sel_hi:[1,0]
	v_cvt_pk_bf16_f32 v158, v94, v95
	v_cvt_pk_bf16_f32 v159, v96, v97
	v_cvt_pk_bf16_f32 v160, v90, v91
	v_cvt_pk_bf16_f32 v161, v92, v93
	s_add_u32 s72, s24, 0x20000
	s_addc_u32 s73, s25, 0
	global_store_dwordx4 v146, v[158:161], s[72:73] offset:0
	v_mul_f32_e32 v175, v95, v95
	v_mul_f32_e32 v253, v97, v97
	v_fmac_f32_e32 v175, v94, v94
	v_fmac_f32_e32 v253, v96, v96
	v_add_f32_e32 v147, v175, v253
	v_mul_f32_e32 v253, v91, v91
	v_fmac_f32_e32 v253, v90, v90
	v_mul_f32_e32 v175, v93, v93
	v_add_f32_e32 v147, v253, v147
	v_fmac_f32_e32 v175, v92, v92
	v_add_f32_e32 v147, v175, v147
	v_pk_mul_f32 v[86:87], v[86:87], v[134:135] op_sel_hi:[1,0]
	v_pk_mul_f32 v[88:89], v[88:89], v[134:135] op_sel_hi:[1,0]
	v_pk_mul_f32 v[82:83], v[82:83], v[134:135] op_sel_hi:[1,0]
	v_pk_mul_f32 v[84:85], v[84:85], v[134:135] op_sel_hi:[1,0]
	v_cvt_pk_bf16_f32 v162, v86, v87
	v_cvt_pk_bf16_f32 v163, v88, v89
	v_cvt_pk_bf16_f32 v164, v82, v83
	v_cvt_pk_bf16_f32 v165, v84, v85
	global_store_dwordx4 v146, v[162:165], s[72:73] offset:256
	v_mul_f32_e32 v175, v87, v87
	v_mul_f32_e32 v253, v89, v89
	v_fmac_f32_e32 v175, v86, v86
	v_fmac_f32_e32 v253, v88, v88
	v_add_f32_e32 v166, v175, v253
	v_mul_f32_e32 v253, v83, v83
	v_fmac_f32_e32 v253, v82, v82
	v_mul_f32_e32 v175, v85, v85
	v_add_f32_e32 v166, v253, v166
	v_fmac_f32_e32 v175, v84, v84
	v_add_f32_e32 v166, v175, v166
	v_add_f32_e32 v166, v147, v166
	s_waitcnt lgkmcnt(0)
	v_add_f32_e32 v168, v168, v169
	v_mov_b32_e32 v169, v168
	s_nop 1
	v_permlane32_swap_b32_e32 v168, v169
	s_and_saveexec_b64 s[6:7], s[8:9]
	v_add_f32_e32 v168, v168, v169
	v_lshlrev_b32_e32 v169, 2, v1
	global_atomic_add_f32 v169, v168, s[26:27] offset:64
	s_mov_b64 exec, s[6:7]
	ds_bpermute_b32 v167, v172, v166
	v_pk_mul_f32 v[78:79], v[78:79], v[136:137] op_sel_hi:[1,0]
	v_pk_mul_f32 v[80:81], v[80:81], v[136:137] op_sel_hi:[1,0]
	v_pk_mul_f32 v[74:75], v[74:75], v[136:137] op_sel_hi:[1,0]
	v_pk_mul_f32 v[76:77], v[76:77], v[136:137] op_sel_hi:[1,0]
	v_cvt_pk_bf16_f32 v158, v78, v79
	v_cvt_pk_bf16_f32 v159, v80, v81
	v_cvt_pk_bf16_f32 v160, v74, v75
	v_cvt_pk_bf16_f32 v161, v76, v77
	s_add_u32 s72, s24, 0x30000
	s_addc_u32 s73, s25, 0
	global_store_dwordx4 v146, v[158:161], s[72:73] offset:0
	v_mul_f32_e32 v175, v79, v79
	v_mul_f32_e32 v253, v81, v81
	v_fmac_f32_e32 v175, v78, v78
	v_fmac_f32_e32 v253, v80, v80
	v_add_f32_e32 v147, v175, v253
	v_mul_f32_e32 v253, v75, v75
	v_fmac_f32_e32 v253, v74, v74
	v_mul_f32_e32 v175, v77, v77
	v_add_f32_e32 v147, v253, v147
	v_fmac_f32_e32 v175, v76, v76
	v_add_f32_e32 v147, v175, v147
	v_pk_mul_f32 v[70:71], v[70:71], v[136:137] op_sel_hi:[1,0]
	v_pk_mul_f32 v[72:73], v[72:73], v[136:137] op_sel_hi:[1,0]
	v_pk_mul_f32 v[66:67], v[66:67], v[136:137] op_sel_hi:[1,0]
	v_pk_mul_f32 v[68:69], v[68:69], v[136:137] op_sel_hi:[1,0]
	v_cvt_pk_bf16_f32 v162, v70, v71
	v_cvt_pk_bf16_f32 v163, v72, v73
	v_cvt_pk_bf16_f32 v164, v66, v67
	v_cvt_pk_bf16_f32 v165, v68, v69
	global_store_dwordx4 v146, v[162:165], s[72:73] offset:256
	v_mul_f32_e32 v175, v71, v71
	v_mul_f32_e32 v253, v73, v73
	v_fmac_f32_e32 v175, v70, v70
	v_fmac_f32_e32 v253, v72, v72
	v_add_f32_e32 v168, v175, v253
	v_mul_f32_e32 v253, v67, v67
	v_fmac_f32_e32 v253, v66, v66
	v_mul_f32_e32 v175, v69, v69
	v_add_f32_e32 v168, v253, v168
	v_fmac_f32_e32 v175, v68, v68
	v_add_f32_e32 v168, v175, v168
	v_add_f32_e32 v168, v147, v168
	s_waitcnt lgkmcnt(0)
; #define GAS __attribute__((address_space(1)))
; __device__ __forceinline__ unsigned cvt_pk_bf16(float lo, float hi) { unsigned r; asm volatile("v_cvt_pk_bf16_f32 %0, %1, %2" : "=v"(r) : "v"(lo), "v"(hi)); return r; }
; __device__ __forceinline__ float bf_lo(unsigned w) { return __uint_as_float(w << 16); }
; __device__ __forceinline__ float bf_hi(unsigned w) { return __uint_as_float(w & 0xffff0000u); }
;     __device__ __forceinline__ void operator()(const f32x4 (&acc)[2][2][4][2], const Unit& u, int wr, int wc, int fr, int fq, const PG8_LAS float* tab) const {
; #pragma unroll
;         for (int ai = 0; ai < 2; ++ai)
; #pragma unroll
;             for (int m = 0; m < 4; ++m) {
;                 const int row = u.pm * BM + ai * HALF + wr * 64 + m * 16 + fr;
;                 const float ra = tab[ai * HALF + wr * 64 + m * 16 + fr];
;                 const GAS float* xo = (const GAS float*)(row < 16384 ? x0a + (size_t)row * 2048 : x0b + (size_t)(row - 16384) * 2048);
;                 GAS bf16_t* xr = (GAS bf16_t*)XN + (size_t)row * 2048;
;                 float ssq = 0.f;
; #pragma unroll
;                 for (int bj = 0; bj < 2; ++bj) {
;                     const int col0 = u.pn * BM + bj * HALF + wc * 32 + 8 * fq;
;                     f32x4 a0, a1;
;                     if (mode == 0) { a0 = *(const GAS f32x4*)(xo + col0); a1 = *(const GAS f32x4*)(xo + col0 + 4); }
;                     else { const u32x4 w = *(const GAS u32x4*)(xr + col0);
;                         a0 = (f32x4){bf_lo(w.x), bf_hi(w.x), bf_lo(w.y), bf_hi(w.y)}; a1 = (f32x4){bf_lo(w.z), bf_hi(w.z), bf_lo(w.w), bf_hi(w.w)}; }
;                     const f32x4 v0 = a0 + acc[ai][bj][m][0] * ra, v1 = a1 + acc[ai][bj][m][1] * ra;
;                     ssq += (v0[0] * v0[0] + v0[1] * v0[1]) + (v0[2] * v0[2] + v0[3] * v0[3]) + (v1[0] * v1[0] + v1[1] * v1[1]) + (v1[2] * v1[2] + v1[3] * v1[3]);
;                     u32x4 w; w.x = cvt_pk_bf16(v0[0], v0[1]); w.y = cvt_pk_bf16(v0[2], v0[3]); w.z = cvt_pk_bf16(v1[0], v1[1]); w.w = cvt_pk_bf16(v1[2], v1[3]);
;                     *(GAS u32x4*)(xr + col0) = w;
;                 }
;                 { const int ln = fr + 16 * fq; ssq += shx(ssq, ln, 16); ssq = x32_sum(ssq); }
;                 if (fq == 0) unsafeAtomicAdd(SSn + row, ssq);
	v_add_f32_e32 v166, v166, v167
	v_mov_b32_e32 v167, v166
	s_nop 1
	v_permlane32_swap_b32_e32 v166, v167
	s_and_saveexec_b64 s[6:7], s[8:9]
	v_add_f32_e32 v166, v166, v167
	v_lshlrev_b32_e32 v167, 2, v1
	global_atomic_add_f32 v167, v166, s[26:27] offset:128
	s_mov_b64 exec, s[6:7]
	ds_bpermute_b32 v169, v172, v168
	v_mov_b32_e32 v130, v131
	v_mov_b32_e32 v132, v133
	v_mov_b32_e32 v134, v135
	v_mov_b32_e32 v136, v137
	v_pk_mul_f32 v[62:63], v[62:63], v[130:131] op_sel_hi:[1,0]
	v_pk_mul_f32 v[64:65], v[64:65], v[130:131] op_sel_hi:[1,0]
	v_pk_mul_f32 v[58:59], v[58:59], v[130:131] op_sel_hi:[1,0]
	v_pk_mul_f32 v[60:61], v[60:61], v[130:131] op_sel_hi:[1,0]
	v_cvt_pk_bf16_f32 v158, v62, v63
	v_cvt_pk_bf16_f32 v159, v64, v65
	v_cvt_pk_bf16_f32 v160, v58, v59
	v_cvt_pk_bf16_f32 v161, v60, v61
	s_add_u32 s72, s24, 0x80000
	s_addc_u32 s73, s25, 0
	global_store_dwordx4 v146, v[158:161], s[72:73] offset:0
	v_mul_f32_e32 v175, v63, v63
	v_mul_f32_e32 v253, v65, v65
	v_fmac_f32_e32 v175, v62, v62
	v_fmac_f32_e32 v253, v64, v64
	v_add_f32_e32 v147, v175, v253
	v_mul_f32_e32 v253, v59, v59
	v_fmac_f32_e32 v253, v58, v58
	v_mul_f32_e32 v175, v61, v61
	v_add_f32_e32 v147, v253, v147
	v_fmac_f32_e32 v175, v60, v60
	v_add_f32_e32 v147, v175, v147
	v_pk_mul_f32 v[54:55], v[54:55], v[130:131] op_sel_hi:[1,0]
	v_pk_mul_f32 v[56:57], v[56:57], v[130:131] op_sel_hi:[1,0]
	v_pk_mul_f32 v[50:51], v[50:51], v[130:131] op_sel_hi:[1,0]
	v_pk_mul_f32 v[52:53], v[52:53], v[130:131] op_sel_hi:[1,0]
	v_cvt_pk_bf16_f32 v162, v54, v55
	v_cvt_pk_bf16_f32 v163, v56, v57
	v_cvt_pk_bf16_f32 v164, v50, v51
	v_cvt_pk_bf16_f32 v165, v52, v53
	global_store_dwordx4 v146, v[162:165], s[72:73] offset:256
	v_mul_f32_e32 v175, v55, v55
	v_mul_f32_e32 v253, v57, v57
	v_fmac_f32_e32 v175, v54, v54
	v_fmac_f32_e32 v253, v56, v56
	v_add_f32_e32 v166, v175, v253
	v_mul_f32_e32 v253, v51, v51
	v_fmac_f32_e32 v253, v50, v50
	v_mul_f32_e32 v175, v53, v53
	v_add_f32_e32 v166, v253, v166
	v_fmac_f32_e32 v175, v52, v52
	v_add_f32_e32 v166, v175, v166
	v_add_f32_e32 v166, v147, v166
	s_waitcnt lgkmcnt(0)
	v_add_f32_e32 v168, v168, v169
	v_mov_b32_e32 v169, v168
	s_nop 1
	v_permlane32_swap_b32_e32 v168, v169
	s_and_saveexec_b64 s[6:7], s[8:9]
	v_add_f32_e32 v168, v168, v169
	v_lshlrev_b32_e32 v169, 2, v1
	global_atomic_add_f32 v169, v168, s[26:27] offset:192
	s_mov_b64 exec, s[6:7]
	ds_bpermute_b32 v167, v172, v166
	v_pk_mul_f32 v[46:47], v[46:47], v[132:133] op_sel_hi:[1,0]
	v_pk_mul_f32 v[48:49], v[48:49], v[132:133] op_sel_hi:[1,0]
	v_pk_mul_f32 v[42:43], v[42:43], v[132:133] op_sel_hi:[1,0]
	v_pk_mul_f32 v[44:45], v[44:45], v[132:133] op_sel_hi:[1,0]
	v_cvt_pk_bf16_f32 v158, v46, v47
	v_cvt_pk_bf16_f32 v159, v48, v49
	v_cvt_pk_bf16_f32 v160, v42, v43
	v_cvt_pk_bf16_f32 v161, v44, v45
	s_add_u32 s72, s24, 0x90000
	s_addc_u32 s73, s25, 0
	global_store_dwordx4 v146, v[158:161], s[72:73] offset:0
	v_mul_f32_e32 v175, v47, v47
	v_mul_f32_e32 v253, v49, v49
	v_fmac_f32_e32 v175, v46, v46
	v_fmac_f32_e32 v253, v48, v48
	v_add_f32_e32 v147, v175, v253
	v_mul_f32_e32 v253, v43, v43
	v_fmac_f32_e32 v253, v42, v42
	v_mul_f32_e32 v175, v45, v45
	v_add_f32_e32 v147, v253, v147
	v_fmac_f32_e32 v175, v44, v44
	v_add_f32_e32 v147, v175, v147
	v_pk_mul_f32 v[38:39], v[38:39], v[132:133] op_sel_hi:[1,0]
	v_pk_mul_f32 v[40:41], v[40:41], v[132:133] op_sel_hi:[1,0]
	v_pk_mul_f32 v[34:35], v[34:35], v[132:133] op_sel_hi:[1,0]
	v_pk_mul_f32 v[36:37], v[36:37], v[132:133] op_sel_hi:[1,0]
	v_cvt_pk_bf16_f32 v162, v38, v39
	v_cvt_pk_bf16_f32 v163, v40, v41
	v_cvt_pk_bf16_f32 v164, v34, v35
	v_cvt_pk_bf16_f32 v165, v36, v37
	global_store_dwordx4 v146, v[162:165], s[72:73] offset:256
	v_mul_f32_e32 v175, v39, v39
	v_mul_f32_e32 v253, v41, v41
	v_fmac_f32_e32 v175, v38, v38
	v_fmac_f32_e32 v253, v40, v40
	v_add_f32_e32 v168, v175, v253
	v_mul_f32_e32 v253, v35, v35
	v_fmac_f32_e32 v253, v34, v34
	v_mul_f32_e32 v175, v37, v37
	v_add_f32_e32 v168, v253, v168
	v_fmac_f32_e32 v175, v36, v36
	v_add_f32_e32 v168, v175, v168
	v_add_f32_e32 v168, v147, v168
	s_waitcnt lgkmcnt(0)
; #define GAS __attribute__((address_space(1)))
; __device__ __forceinline__ unsigned cvt_pk_bf16(float lo, float hi) { unsigned r; asm volatile("v_cvt_pk_bf16_f32 %0, %1, %2" : "=v"(r) : "v"(lo), "v"(hi)); return r; }
; __device__ __forceinline__ float bf_lo(unsigned w) { return __uint_as_float(w << 16); }
; __device__ __forceinline__ float bf_hi(unsigned w) { return __uint_as_float(w & 0xffff0000u); }
;     __device__ __forceinline__ void operator()(const f32x4 (&acc)[2][2][4][2], const Unit& u, int wr, int wc, int fr, int fq, const PG8_LAS float* tab) const {
; #pragma unroll
;         for (int ai = 0; ai < 2; ++ai)
; #pragma unroll
;             for (int m = 0; m < 4; ++m) {
;                 const int row = u.pm * BM + ai * HALF + wr * 64 + m * 16 + fr;
;                 const float ra = tab[ai * HALF + wr * 64 + m * 16 + fr];
;                 const GAS float* xo = (const GAS float*)(row < 16384 ? x0a + (size_t)row * 2048 : x0b + (size_t)(row - 16384) * 2048);
;                 GAS bf16_t* xr = (GAS bf16_t*)XN + (size_t)row * 2048;
;                 float ssq = 0.f;
; #pragma unroll
;                 for (int bj = 0; bj < 2; ++bj) {
;                     const int col0 = u.pn * BM + bj * HALF + wc * 32 + 8 * fq;
;                     f32x4 a0, a1;
;                     if (mode == 0) { a0 = *(const GAS f32x4*)(xo + col0); a1 = *(const GAS f32x4*)(xo + col0 + 4); }
;                     else { const u32x4 w = *(const GAS u32x4*)(xr + col0);
;                         a0 = (f32x4){bf_lo(w.x), bf_hi(w.x), bf_lo(w.y), bf_hi(w.y)}; a1 = (f32x4){bf_lo(w.z), bf_hi(w.z), bf_lo(w.w), bf_hi(w.w)}; }
;                     const f32x4 v0 = a0 + acc[ai][bj][m][0] * ra, v1 = a1 + acc[ai][bj][m][1] * ra;
;                     ssq += (v0[0] * v0[0] + v0[1] * v0[1]) + (v0[2] * v0[2] + v0[3] * v0[3]) + (v1[0] * v1[0] + v1[1] * v1[1]) + (v1[2] * v1[2] + v1[3] * v1[3]);
;                     u32x4 w; w.x = cvt_pk_bf16(v0[0], v0[1]); w.y = cvt_pk_bf16(v0[2], v0[3]); w.z = cvt_pk_bf16(v1[0], v1[1]); w.w = cvt_pk_bf16(v1[2], v1[3]);
;                     *(GAS u32x4*)(xr + col0) = w;
;                 }
;                 { const int ln = fr + 16 * fq; ssq += shx(ssq, ln, 16); ssq = x32_sum(ssq); }
;                 if (fq == 0) unsafeAtomicAdd(SSn + row, ssq);
	v_add_f32_e32 v166, v166, v167
	v_mov_b32_e32 v167, v166
	s_nop 1
	v_permlane32_swap_b32_e32 v166, v167
	s_and_saveexec_b64 s[6:7], s[8:9]
	v_add_f32_e32 v166, v166, v167
	v_lshlrev_b32_e32 v167, 2, v1
	global_atomic_add_f32 v167, v166, s[26:27] offset:512
	s_mov_b64 exec, s[6:7]
	ds_bpermute_b32 v169, v172, v168
	v_pk_mul_f32 v[30:31], v[30:31], v[134:135] op_sel_hi:[1,0]
	v_pk_mul_f32 v[32:33], v[32:33], v[134:135] op_sel_hi:[1,0]
	v_pk_mul_f32 v[26:27], v[26:27], v[134:135] op_sel_hi:[1,0]
	v_pk_mul_f32 v[28:29], v[28:29], v[134:135] op_sel_hi:[1,0]
	v_cvt_pk_bf16_f32 v158, v30, v31
	v_cvt_pk_bf16_f32 v159, v32, v33
	v_cvt_pk_bf16_f32 v160, v26, v27
	v_cvt_pk_bf16_f32 v161, v28, v29
	s_add_u32 s72, s24, 0xa0000
	s_addc_u32 s73, s25, 0
	global_store_dwordx4 v146, v[158:161], s[72:73] offset:0
	v_mul_f32_e32 v175, v31, v31
	v_mul_f32_e32 v253, v33, v33
	v_fmac_f32_e32 v175, v30, v30
	v_fmac_f32_e32 v253, v32, v32
	v_add_f32_e32 v147, v175, v253
	v_mul_f32_e32 v253, v27, v27
	v_fmac_f32_e32 v253, v26, v26
	v_mul_f32_e32 v175, v29, v29
	v_add_f32_e32 v147, v253, v147
	v_fmac_f32_e32 v175, v28, v28
	v_add_f32_e32 v147, v175, v147
	v_pk_mul_f32 v[22:23], v[22:23], v[134:135] op_sel_hi:[1,0]
	v_pk_mul_f32 v[24:25], v[24:25], v[134:135] op_sel_hi:[1,0]
	v_pk_mul_f32 v[18:19], v[18:19], v[134:135] op_sel_hi:[1,0]
	v_pk_mul_f32 v[20:21], v[20:21], v[134:135] op_sel_hi:[1,0]
	v_cvt_pk_bf16_f32 v162, v22, v23
	v_cvt_pk_bf16_f32 v163, v24, v25
	v_cvt_pk_bf16_f32 v164, v18, v19
	v_cvt_pk_bf16_f32 v165, v20, v21
	global_store_dwordx4 v146, v[162:165], s[72:73] offset:256
	v_mul_f32_e32 v175, v23, v23
	v_mul_f32_e32 v253, v25, v25
	v_fmac_f32_e32 v175, v22, v22
	v_fmac_f32_e32 v253, v24, v24
	v_add_f32_e32 v166, v175, v253
	v_mul_f32_e32 v253, v19, v19
	v_fmac_f32_e32 v253, v18, v18
	v_mul_f32_e32 v175, v21, v21
	v_add_f32_e32 v166, v253, v166
	v_fmac_f32_e32 v175, v20, v20
	v_add_f32_e32 v166, v175, v166
	v_add_f32_e32 v166, v147, v166
	s_waitcnt lgkmcnt(0)
	v_add_f32_e32 v168, v168, v169
	v_mov_b32_e32 v169, v168
	s_nop 1
	v_permlane32_swap_b32_e32 v168, v169
	s_and_saveexec_b64 s[6:7], s[8:9]
	v_add_f32_e32 v168, v168, v169
	v_lshlrev_b32_e32 v169, 2, v1
	global_atomic_add_f32 v169, v168, s[26:27] offset:576
	s_mov_b64 exec, s[6:7]
	ds_bpermute_b32 v167, v172, v166
	v_pk_mul_f32 v[14:15], v[14:15], v[136:137] op_sel_hi:[1,0]
	v_pk_mul_f32 v[16:17], v[16:17], v[136:137] op_sel_hi:[1,0]
	v_pk_mul_f32 v[10:11], v[10:11], v[136:137] op_sel_hi:[1,0]
	v_pk_mul_f32 v[12:13], v[12:13], v[136:137] op_sel_hi:[1,0]
	v_cvt_pk_bf16_f32 v158, v14, v15
	v_cvt_pk_bf16_f32 v159, v16, v17
	v_cvt_pk_bf16_f32 v160, v10, v11
	v_cvt_pk_bf16_f32 v161, v12, v13
	s_add_u32 s72, s24, 0xb0000
	s_addc_u32 s73, s25, 0
	global_store_dwordx4 v146, v[158:161], s[72:73] offset:0
	v_mul_f32_e32 v175, v15, v15
	v_mul_f32_e32 v253, v17, v17
	v_fmac_f32_e32 v175, v14, v14
	v_fmac_f32_e32 v253, v16, v16
	v_add_f32_e32 v147, v175, v253
	v_mul_f32_e32 v253, v11, v11
	v_fmac_f32_e32 v253, v10, v10
	v_mul_f32_e32 v175, v13, v13
	v_add_f32_e32 v147, v253, v147
	v_fmac_f32_e32 v175, v12, v12
	v_add_f32_e32 v147, v175, v147
	v_pk_mul_f32 v[6:7], v[6:7], v[136:137] op_sel_hi:[1,0]
	v_pk_mul_f32 v[8:9], v[8:9], v[136:137] op_sel_hi:[1,0]
	v_pk_mul_f32 v[2:3], v[2:3], v[136:137] op_sel_hi:[1,0]
	v_pk_mul_f32 v[4:5], v[4:5], v[136:137] op_sel_hi:[1,0]
	v_cvt_pk_bf16_f32 v162, v6, v7
	v_cvt_pk_bf16_f32 v163, v8, v9
	v_cvt_pk_bf16_f32 v164, v2, v3
	v_cvt_pk_bf16_f32 v165, v4, v5
	global_store_dwordx4 v146, v[162:165], s[72:73] offset:256
	v_mul_f32_e32 v175, v7, v7
	v_mul_f32_e32 v253, v9, v9
	v_fmac_f32_e32 v175, v6, v6
	v_fmac_f32_e32 v253, v8, v8
	v_add_f32_e32 v168, v175, v253
	v_mul_f32_e32 v253, v3, v3
	v_fmac_f32_e32 v253, v2, v2
	v_mul_f32_e32 v175, v5, v5
	v_add_f32_e32 v168, v253, v168
	v_fmac_f32_e32 v175, v4, v4
	v_add_f32_e32 v168, v175, v168
	v_add_f32_e32 v168, v147, v168
	s_waitcnt lgkmcnt(0)
	v_add_f32_e32 v166, v166, v167
	v_mov_b32_e32 v167, v166
	s_nop 1
	v_permlane32_swap_b32_e32 v166, v167
	s_and_saveexec_b64 s[6:7], s[8:9]
	v_add_f32_e32 v166, v166, v167
	v_lshlrev_b32_e32 v167, 2, v1
	global_atomic_add_f32 v167, v166, s[26:27] offset:640
	s_mov_b64 exec, s[6:7]
	ds_bpermute_b32 v169, v172, v168
	s_waitcnt lgkmcnt(0)
	v_add_f32_e32 v168, v168, v169
	v_mov_b32_e32 v169, v168
	s_nop 1
	v_permlane32_swap_b32_e32 v168, v169
	s_and_saveexec_b64 s[6:7], s[8:9]
	v_add_f32_e32 v168, v168, v169
	v_lshlrev_b32_e32 v169, 2, v1
	global_atomic_add_f32 v169, v168, s[26:27] offset:704
	s_mov_b64 exec, s[6:7]
	s_and_b64 vcc, exec, s[4:5]
	s_mov_b64 s[4:5], -1
	s_cbranch_vccnz .LBB0_596
	s_andn2_b64 vcc, exec, s[10:11]
	s_cbranch_vccnz .LBB0_595
	s_barrier
	s_branch .LBB0_595

; __global__ void __launch_bounds__(NTHREADS, 2) __attribute__((amdgpu_waves_per_eu(2, 2))) hymba_fwd(Params p) {
	.amdhsa_kernel _Z9hymba_fwd6Params
		.amdhsa_group_segment_fixed_size 0
		.amdhsa_private_segment_fixed_size 0
		.amdhsa_kernarg_size 392
		.amdhsa_user_sgpr_count 2
		.amdhsa_user_sgpr_dispatch_ptr 0
		.amdhsa_user_sgpr_queue_ptr 0
		.amdhsa_user_sgpr_kernarg_segment_ptr 1
		.amdhsa_user_sgpr_dispatch_id 0
		.amdhsa_user_sgpr_kernarg_preload_length 0
		.amdhsa_user_sgpr_kernarg_preload_offset 0
		.amdhsa_user_sgpr_private_segment_size 0
		.amdhsa_uses_dynamic_stack 0
		.amdhsa_enable_private_segment 0
		.amdhsa_system_sgpr_workgroup_id_x 1
		.amdhsa_system_sgpr_workgroup_id_y 0
		.amdhsa_system_sgpr_workgroup_id_z 0
		.amdhsa_system_sgpr_workgroup_info 0
		.amdhsa_system_vgpr_workitem_id 2
		.amdhsa_next_free_vgpr 255
		.amdhsa_next_free_sgpr 102
		.amdhsa_accum_offset 256
		.amdhsa_reserve_vcc 1
		.amdhsa_float_round_mode_32 0
		.amdhsa_float_round_mode_16_64 0
		.amdhsa_float_denorm_mode_32 3
		.amdhsa_float_denorm_mode_16_64 3
		.amdhsa_dx10_clamp 1
		.amdhsa_ieee_mode 1
		.amdhsa_fp16_overflow 0
		.amdhsa_tg_split 0
		.amdhsa_exception_fp_ieee_invalid_op 0
		.amdhsa_exception_fp_denorm_src 0
		.amdhsa_exception_fp_ieee_div_zero 0
		.amdhsa_exception_fp_ieee_overflow 0
		.amdhsa_exception_fp_ieee_underflow 0
		.amdhsa_exception_fp_ieee_inexact 0
		.amdhsa_exception_int_div_zero 0
	.end_amdhsa_kernel

; __global__ void __launch_bounds__(NTHREADS, 2) __attribute__((amdgpu_waves_per_eu(2, 2))) hymba_fwd(Params p) {
amdhsa.kernels:
  - .agpr_count:     0
    .args:
      - .offset:         0
        .size:           136
        .value_kind:     by_value
      - .offset:         136
        .size:           4
        .value_kind:     hidden_block_count_x
      - .offset:         140
        .size:           4
        .value_kind:     hidden_block_count_y
      - .offset:         144
        .size:           4
        .value_kind:     hidden_block_count_z
      - .offset:         148
        .size:           2
        .value_kind:     hidden_group_size_x
      - .offset:         150
        .size:           2
        .value_kind:     hidden_group_size_y
      - .offset:         152
        .size:           2
        .value_kind:     hidden_group_size_z
      - .offset:         154
        .size:           2
        .value_kind:     hidden_remainder_x
      - .offset:         156
        .size:           2
        .value_kind:     hidden_remainder_y
      - .offset:         158
        .size:           2
        .value_kind:     hidden_remainder_z
      - .offset:         176
        .size:           8
        .value_kind:     hidden_global_offset_x
      - .offset:         184
        .size:           8
        .value_kind:     hidden_global_offset_y
      - .offset:         192
        .size:           8
        .value_kind:     hidden_global_offset_z
      - .offset:         200
        .size:           2
        .value_kind:     hidden_grid_dims
      - .offset:         224
        .size:           8
        .value_kind:     hidden_multigrid_sync_arg
      - .offset:         256
        .size:           4
        .value_kind:     hidden_dynamic_lds_size
    .group_segment_fixed_size: 0
    .kernarg_segment_align: 8
    .kernarg_segment_size: 392
    .language:       OpenCL C
    .language_version:
      - 2
      - 0
    .max_flat_workgroup_size: 512
    .name:           _Z9hymba_fwd6Params
    .private_segment_fixed_size: 0
    .sgpr_count:     108
    .sgpr_spill_count: 43
    .symbol:         _Z9hymba_fwd6Params.kd
    .uniform_work_group_size: 1
    .uses_dynamic_stack: false
    .vgpr_count:     255
    .vgpr_spill_count: 0
    .wavefront_size: 64
